# P6 up-GEMM: hand-written conv3+SiLU epilogue (A rows permuted at staging so the token conv runs mostly in-lane: 2 DPP + 12 FMA per 4 rows), plus earlier P2/P3/P5/P9 wait fixes
# speedup vs baseline: 1.0258x; 1.0187x over previous
; __device__ __forceinline__ unsigned cvtpk(float lo, float hi) { f32x2_t v = {lo, hi}; bf16x2_t b = __builtin_convertvector(v, bf16x2_t); return __builtin_bit_cast(unsigned, b); }
; __global__ void __launch_bounds__(NTHREADS, 2) fwd_megakernel(Args args) {
;     ...
;         for (size_t it = gt; it < nitems; it += NGT) {
;             const size_t tok0 = (it >> 7) * TB; const int ac = (int)(it & 127), h = ac >> 4, c0 = ac * 8;
; #pragma unroll 4
;             for (int t = 0; t < TB; ++t) {
;                 const size_t tok = tok0 + t;
;                 const float l0 = LSE[tok * 8 + h], l1 = LSE[(size_t)MTOK * 8 + tok * 8 + h], l2 = LSE[(size_t)2 * MTOK * 8 + tok * 8 + h];
;                 const float mm = fmaxf(l0, fmaxf(l1, l2));
;                 float w0 = __builtin_amdgcn_exp2f(l0 - mm), w1 = __builtin_amdgcn_exp2f(l1 - mm), w2 = __builtin_amdgcn_exp2f(l2 - mm);
;                 const float inv = 1.0f / (w0 + w1 + w2); w0 *= inv; w1 *= inv; w2 *= inv;
;                 const v4u a0 = *(const v4u*)(OG0 + tok * 1024 + c0), a1 = *(const v4u*)(OG1 + tok * 1024 + c0), a2 = *(const v4u*)(OG2 + tok * 1024 + c0);
;                 v4u o;
;                 o.x = cvtpk(w0 * bflo(a0.x) + w1 * bflo(a1.x) + w2 * bflo(a2.x), w0 * bfhi(a0.x) + w1 * bfhi(a1.x) + w2 * bfhi(a2.x));
;                 o.y = cvtpk(w0 * bflo(a0.y) + w1 * bflo(a1.y) + w2 * bflo(a2.y), w0 * bfhi(a0.y) + w1 * bfhi(a1.y) + w2 * bfhi(a2.y));
;                 o.z = cvtpk(w0 * bflo(a0.z) + w1 * bflo(a1.z) + w2 * bflo(a2.z), w0 * bfhi(a0.z) + w1 * bfhi(a1.z) + w2 * bfhi(a2.z));
;                 o.w = cvtpk(w0 * bflo(a0.w) + w1 * bflo(a1.w) + w2 * bflo(a2.w), w0 * bfhi(a0.w) + w1 * bfhi(a1.w) + w2 * bfhi(a2.w));
;                 *(v4u*)(YMIX + tok * DM + CONVW + c0) = o;
;             }
.LBB0_209:
	v_lshl_add_u64 v[20:21], s[40:41], 0, v[12:13]
	v_add_co_u32_e64 v28, s[4:5], s33, v20
	v_lshl_add_u64 v[26:27], s[40:41], 0, v[14:15]
	s_nop 0
	v_addc_co_u32_e64 v29, s[4:5], 0, v21, s[4:5]
	v_add_co_u32_e64 v18, s[4:5], s63, v20
	v_lshl_add_u64 v[22:23], s[38:39], 0, v[12:13]
	s_nop 0
	v_addc_co_u32_e64 v19, s[4:5], 0, v21, s[4:5]
	v_add_co_u32_e64 v30, s[4:5], s46, v20
	v_add_co_u32_e32 v24, vcc, 0x3fc00000, v26
	s_nop 0
	v_addc_co_u32_e64 v31, s[4:5], 0, v21, s[4:5]
	v_add_co_u32_e64 v20, s[4:5], s64, v20
	v_addc_co_u32_e32 v25, vcc, 0, v27, vcc
	s_nop 0
	v_addc_co_u32_e64 v21, s[4:5], 0, v21, s[4:5]
	v_add_co_u32_e64 v32, s[4:5], s47, v22
	v_add_co_u32_e32 v50, vcc, 0x3fd00000, v26
	s_nop 0
	v_addc_co_u32_e64 v33, s[4:5], 0, v23, s[4:5]
	v_add_co_u32_e64 v22, s[4:5], s65, v22
	v_addc_co_u32_e32 v51, vcc, 0, v27, vcc
	s_nop 0
	v_addc_co_u32_e64 v23, s[4:5], 0, v23, s[4:5]
	global_load_dwordx4 v[36:39], v[20:21], off offset:-4096
	global_load_dwordx4 v[40:43], v[22:23], off offset:-4096
	global_load_dword v68, v[24:25], off
	v_add_co_u32_e32 v52, vcc, 0x3fe00000, v26
	v_lshl_add_u64 v[16:17], s[38:39], 0, v[10:11]
	s_nop 0
	v_addc_co_u32_e32 v53, vcc, 0, v27, vcc
	global_load_dword v69, v[50:51], off
	global_load_dword v70, v[52:53], off
	global_load_dwordx4 v[44:47], v[18:19], off offset:-4096
	v_add_co_u32_e64 v82, s[4:5], s62, v16
	s_add_i32 s67, s67, -4
	s_nop 0
	v_addc_co_u32_e64 v83, s[4:5], 0, v17, s[4:5]
	v_add_co_u32_e64 v48, s[4:5], s66, v16
	v_lshl_add_u64 v[10:11], v[10:11], 0, s[10:11]
	s_nop 0
	v_addc_co_u32_e64 v49, s[4:5], 0, v17, s[4:5]
	v_lshl_add_u64 v[12:13], v[12:13], 0, s[56:57]
	v_lshl_add_u64 v[14:15], v[14:15], 0, s[58:59]
	s_cmp_eq_u32 s67, 0
	s_waitcnt vmcnt(5)
	v_lshlrev_b32_e32 v26, 16, v36
	v_and_b32_e32 v55, 0xffff0000, v36
	v_lshlrev_b32_e32 v36, 16, v37
	v_and_b32_e32 v59, 0xffff0000, v37
	v_lshlrev_b32_e32 v60, 16, v38
	v_and_b32_e32 v63, 0xffff0000, v38
	v_lshlrev_b32_e32 v38, 16, v39
	s_waitcnt vmcnt(1)
	v_max3_f32 v71, v68, v69, v70
	s_waitcnt vmcnt(0)
	v_and_b32_e32 v27, 0xffff0000, v44
	v_lshlrev_b32_e32 v54, 16, v44
	v_and_b32_e32 v61, 0xffff0000, v46
	v_lshlrev_b32_e32 v62, 16, v46
	v_sub_f32_e32 v44, v68, v71
	v_sub_f32_e32 v46, v69, v71
	v_and_b32_e32 v67, 0xffff0000, v39
	v_and_b32_e32 v37, 0xffff0000, v45
	v_lshlrev_b32_e32 v58, 16, v45
	v_and_b32_e32 v39, 0xffff0000, v47
	v_lshlrev_b32_e32 v66, 16, v47
	v_sub_f32_e32 v47, v70, v71
	v_exp_f32_e32 v45, v44
	v_exp_f32_e32 v44, v46
	v_exp_f32_e32 v47, v47
	v_lshlrev_b32_e32 v56, 16, v40
	v_and_b32_e32 v57, 0xffff0000, v40
	v_add_f32_e32 v46, v45, v44
	v_add_f32_e32 v46, v47, v46
	v_div_scale_f32 v68, s[4:5], v46, v46, 1.0
	v_rcp_f32_e32 v70, v68
	v_div_scale_f32 v69, vcc, 1.0, v46, 1.0
	v_lshlrev_b32_e32 v40, 16, v41
	v_fma_f32 v71, -v68, v70, 1.0
	v_fmac_f32_e32 v70, v71, v70
	v_mul_f32_e32 v71, v69, v70
	v_fma_f32 v72, -v68, v71, v69
	v_fmac_f32_e32 v71, v72, v70
	v_fma_f32 v68, -v68, v71, v69
	v_div_fmas_f32 v68, v68, v70, v71
	v_div_fixup_f32 v46, v68, v46, 1.0
	v_pk_mul_f32 v[44:45], v[44:45], v[46:47] op_sel_hi:[1,0]
	v_mul_f32_e32 v68, v47, v46
	v_pk_mul_f32 v[46:47], v[44:45], v[54:55] op_sel:[1,0] op_sel_hi:[0,1]
	v_pk_mul_f32 v[54:55], v[44:45], v[58:59] op_sel:[1,0] op_sel_hi:[0,1]
	v_pk_mul_f32 v[58:59], v[44:45], v[62:63] op_sel:[1,0] op_sel_hi:[0,1]
	v_pk_mul_f32 v[62:63], v[44:45], v[66:67] op_sel:[1,0] op_sel_hi:[0,1]
	v_and_b32_e32 v41, 0xffff0000, v41
	v_lshlrev_b32_e32 v64, 16, v42
	v_and_b32_e32 v65, 0xffff0000, v42
	v_lshlrev_b32_e32 v42, 16, v43
	v_and_b32_e32 v43, 0xffff0000, v43
	v_pk_fma_f32 v[26:27], v[44:45], v[26:27], v[46:47]
	v_pk_fma_f32 v[36:37], v[44:45], v[36:37], v[54:55]
	v_pk_fma_f32 v[46:47], v[44:45], v[60:61], v[58:59]
	v_pk_fma_f32 v[38:39], v[44:45], v[38:39], v[62:63]
	v_pk_fma_f32 v[26:27], v[68:69], v[56:57], v[26:27] op_sel_hi:[0,1,1]
	v_pk_fma_f32 v[40:41], v[68:69], v[40:41], v[36:37] op_sel_hi:[0,1,1]
	v_pk_fma_f32 v[44:45], v[68:69], v[64:65], v[46:47] op_sel_hi:[0,1,1]
	v_pk_fma_f32 v[42:43], v[68:69], v[42:43], v[38:39] op_sel_hi:[0,1,1]
	v_cvt_pk_bf16_f32 v74, v26, v27
	v_cvt_pk_bf16_f32 v75, v40, v41
	v_cvt_pk_bf16_f32 v76, v44, v45
	v_cvt_pk_bf16_f32 v77, v42, v43
	global_load_dword v60, v[24:25], off offset:32
	global_load_dword v61, v[50:51], off offset:32
	global_load_dword v62, v[52:53], off offset:32
	s_nop 0
	global_load_dwordx4 v[36:39], v[30:31], off offset:2048
	s_nop 0
	global_load_dwordx4 v[26:29], v[28:29], off offset:2048
	s_nop 0
	global_load_dwordx4 v[30:33], v[32:33], off offset:2048
	global_store_dwordx4 v[16:17], v[74:77], off offset:2048
	s_waitcnt vmcnt(4)
	v_max3_f32 v63, v60, v61, v62
	s_waitcnt vmcnt(3)
	v_lshlrev_b32_e32 v40, 16, v36
	v_and_b32_e32 v43, 0xffff0000, v36
	v_lshlrev_b32_e32 v36, 16, v38
	v_and_b32_e32 v55, 0xffff0000, v38
	v_sub_f32_e32 v38, v60, v63
	v_sub_f32_e32 v60, v61, v63
	s_waitcnt vmcnt(2)
	v_and_b32_e32 v41, 0xffff0000, v26
	v_lshlrev_b32_e32 v42, 16, v26
	v_lshlrev_b32_e32 v46, 16, v37
	v_and_b32_e32 v47, 0xffff0000, v27
	v_lshlrev_b32_e32 v26, 16, v27
	v_and_b32_e32 v27, 0xffff0000, v37
	v_and_b32_e32 v37, 0xffff0000, v28
	v_lshlrev_b32_e32 v54, 16, v28
	v_lshlrev_b32_e32 v58, 16, v39
	v_and_b32_e32 v59, 0xffff0000, v29
	v_lshlrev_b32_e32 v28, 16, v29
	v_and_b32_e32 v29, 0xffff0000, v39
	v_sub_f32_e32 v61, v62, v63
	v_exp_f32_e32 v39, v38
	v_exp_f32_e32 v38, v60
	v_exp_f32_e32 v61, v61
	s_waitcnt vmcnt(1)
; __device__ __forceinline__ unsigned cvtpk(float lo, float hi) { f32x2_t v = {lo, hi}; bf16x2_t b = __builtin_convertvector(v, bf16x2_t); return __builtin_bit_cast(unsigned, b); }
; __global__ void __launch_bounds__(NTHREADS, 2) fwd_megakernel(Args args) {
;     ...
;             for (int t = 0; t < TB; ++t) {
;                 const size_t tok = tok0 + t;
;                 const float l0 = LSE[tok * 8 + h], l1 = LSE[(size_t)MTOK * 8 + tok * 8 + h], l2 = LSE[(size_t)2 * MTOK * 8 + tok * 8 + h];
;                 const float mm = fmaxf(l0, fmaxf(l1, l2));
;                 float w0 = __builtin_amdgcn_exp2f(l0 - mm), w1 = __builtin_amdgcn_exp2f(l1 - mm), w2 = __builtin_amdgcn_exp2f(l2 - mm);
;                 const float inv = 1.0f / (w0 + w1 + w2); w0 *= inv; w1 *= inv; w2 *= inv;
;                 const v4u a0 = *(const v4u*)(OG0 + tok * 1024 + c0), a1 = *(const v4u*)(OG1 + tok * 1024 + c0), a2 = *(const v4u*)(OG2 + tok * 1024 + c0);
;                 v4u o;
;                 o.x = cvtpk(w0 * bflo(a0.x) + w1 * bflo(a1.x) + w2 * bflo(a2.x), w0 * bfhi(a0.x) + w1 * bfhi(a1.x) + w2 * bfhi(a2.x));
;                 o.y = cvtpk(w0 * bflo(a0.y) + w1 * bflo(a1.y) + w2 * bflo(a2.y), w0 * bfhi(a0.y) + w1 * bfhi(a1.y) + w2 * bfhi(a2.y));
;                 o.z = cvtpk(w0 * bflo(a0.z) + w1 * bflo(a1.z) + w2 * bflo(a2.z), w0 * bfhi(a0.z) + w1 * bfhi(a1.z) + w2 * bfhi(a2.z));
;                 o.w = cvtpk(w0 * bflo(a0.w) + w1 * bflo(a1.w) + w2 * bflo(a2.w), w0 * bfhi(a0.w) + w1 * bfhi(a1.w) + w2 * bfhi(a2.w));
;                 *(v4u*)(YMIX + tok * DM + CONVW + c0) = o;
	v_lshlrev_b32_e32 v44, 16, v30
	v_and_b32_e32 v45, 0xffff0000, v30
	v_add_f32_e32 v60, v39, v38
	v_add_f32_e32 v60, v61, v60
	v_div_scale_f32 v62, s[4:5], v60, v60, 1.0
	v_rcp_f32_e32 v64, v62
	v_div_scale_f32 v63, vcc, 1.0, v60, 1.0
	v_lshlrev_b32_e32 v30, 16, v31
	v_fma_f32 v65, -v62, v64, 1.0
	v_fmac_f32_e32 v64, v65, v64
	v_mul_f32_e32 v65, v63, v64
	v_fma_f32 v66, -v62, v65, v63
	v_fmac_f32_e32 v65, v66, v64
	v_fma_f32 v62, -v62, v65, v63
	v_div_fmas_f32 v62, v62, v64, v65
	v_div_fixup_f32 v60, v62, v60, 1.0
	v_pk_mul_f32 v[38:39], v[38:39], v[60:61] op_sel_hi:[1,0]
	v_and_b32_e32 v31, 0xffff0000, v31
	v_pk_mul_f32 v[42:43], v[38:39], v[42:43] op_sel:[1,0] op_sel_hi:[0,1]
	v_pk_mul_f32 v[26:27], v[38:39], v[26:27] op_sel:[1,0] op_sel_hi:[0,1]
	v_pk_mul_f32 v[54:55], v[38:39], v[54:55] op_sel:[1,0] op_sel_hi:[0,1]
	v_pk_mul_f32 v[28:29], v[38:39], v[28:29] op_sel:[1,0] op_sel_hi:[0,1]
	v_lshlrev_b32_e32 v56, 16, v32
	v_and_b32_e32 v57, 0xffff0000, v32
	v_lshlrev_b32_e32 v32, 16, v33
	v_and_b32_e32 v33, 0xffff0000, v33
	v_mul_f32_e32 v62, v61, v60
	v_pk_fma_f32 v[40:41], v[38:39], v[40:41], v[42:43]
	v_pk_fma_f32 v[26:27], v[38:39], v[46:47], v[26:27]
	v_pk_fma_f32 v[36:37], v[38:39], v[36:37], v[54:55]
	v_pk_fma_f32 v[28:29], v[38:39], v[58:59], v[28:29]
	v_pk_fma_f32 v[38:39], v[62:63], v[44:45], v[40:41] op_sel_hi:[0,1,1]
	v_pk_fma_f32 v[30:31], v[62:63], v[30:31], v[26:27] op_sel_hi:[0,1,1]
	v_pk_fma_f32 v[36:37], v[62:63], v[56:57], v[36:37] op_sel_hi:[0,1,1]
	v_pk_fma_f32 v[32:33], v[62:63], v[32:33], v[28:29] op_sel_hi:[0,1,1]
	v_cvt_pk_bf16_f32 v78, v38, v39
	v_cvt_pk_bf16_f32 v79, v30, v31
	v_cvt_pk_bf16_f32 v80, v36, v37
	v_cvt_pk_bf16_f32 v81, v32, v33
	global_load_dword v58, v[24:25], off offset:64
	global_load_dword v59, v[50:51], off offset:64
	global_load_dword v60, v[52:53], off offset:64
	s_nop 0
	global_load_dwordx4 v[26:29], v[20:21], off
	global_load_dwordx4 v[30:33], v[18:19], off
	global_load_dwordx4 v[34:37], v[22:23], off
	global_store_dwordx4 v[82:83], v[78:81], off offset:2048
	s_waitcnt vmcnt(4)
	v_max3_f32 v61, v58, v59, v60
	s_waitcnt vmcnt(3)
	v_lshlrev_b32_e32 v38, 16, v26
	s_waitcnt vmcnt(2)
	v_and_b32_e32 v39, 0xffff0000, v30
	s_waitcnt vmcnt(1)
	v_lshlrev_b32_e32 v54, 16, v36
	v_and_b32_e32 v55, 0xffff0000, v36
	v_sub_f32_e32 v36, v58, v61
	v_sub_f32_e32 v58, v59, v61
	v_lshlrev_b32_e32 v40, 16, v30
	v_and_b32_e32 v41, 0xffff0000, v26
	v_lshlrev_b32_e32 v42, 16, v34
	v_and_b32_e32 v43, 0xffff0000, v34
	v_and_b32_e32 v45, 0xffff0000, v31
	v_lshlrev_b32_e32 v26, 16, v31
	v_lshlrev_b32_e32 v30, 16, v35
	v_and_b32_e32 v31, 0xffff0000, v35
	v_lshlrev_b32_e32 v34, 16, v28
	v_and_b32_e32 v35, 0xffff0000, v32
	v_lshlrev_b32_e32 v46, 16, v32
	v_and_b32_e32 v47, 0xffff0000, v28
	v_and_b32_e32 v57, 0xffff0000, v33
	v_lshlrev_b32_e32 v28, 16, v33
	v_lshlrev_b32_e32 v32, 16, v37
	v_and_b32_e32 v33, 0xffff0000, v37
	v_sub_f32_e32 v59, v60, v61
	v_exp_f32_e32 v37, v36
	v_exp_f32_e32 v36, v58
	v_exp_f32_e32 v59, v59
	v_lshlrev_b32_e32 v44, 16, v27
	v_and_b32_e32 v27, 0xffff0000, v27
	v_add_f32_e32 v58, v37, v36
	v_add_f32_e32 v58, v59, v58
	v_div_scale_f32 v60, s[4:5], v58, v58, 1.0
	v_rcp_f32_e32 v62, v60
	v_div_scale_f32 v61, vcc, 1.0, v58, 1.0
	v_lshlrev_b32_e32 v56, 16, v29
	v_fma_f32 v63, -v60, v62, 1.0
	v_fmac_f32_e32 v62, v63, v62
	v_mul_f32_e32 v63, v61, v62
	v_fma_f32 v64, -v60, v63, v61
	v_fmac_f32_e32 v63, v64, v62
	v_fma_f32 v60, -v60, v63, v61
	v_div_fmas_f32 v60, v60, v62, v63
	v_div_fixup_f32 v58, v60, v58, 1.0
	v_and_b32_e32 v29, 0xffff0000, v29
	v_pk_mul_f32 v[36:37], v[36:37], v[58:59] op_sel_hi:[1,0]
	v_mul_f32_e32 v60, v59, v58
	v_pk_mul_f32 v[40:41], v[36:37], v[40:41] op_sel:[1,0] op_sel_hi:[0,1]
	v_pk_mul_f32 v[26:27], v[36:37], v[26:27] op_sel:[1,0] op_sel_hi:[0,1]
	v_pk_mul_f32 v[46:47], v[36:37], v[46:47] op_sel:[1,0] op_sel_hi:[0,1]
	v_pk_mul_f32 v[28:29], v[36:37], v[28:29] op_sel:[1,0] op_sel_hi:[0,1]
	v_pk_fma_f32 v[38:39], v[36:37], v[38:39], v[40:41]
	v_pk_fma_f32 v[26:27], v[36:37], v[44:45], v[26:27]
	v_pk_fma_f32 v[34:35], v[36:37], v[34:35], v[46:47]
	v_pk_fma_f32 v[28:29], v[36:37], v[56:57], v[28:29]
	v_pk_fma_f32 v[36:37], v[60:61], v[42:43], v[38:39] op_sel_hi:[0,1,1]
	v_pk_fma_f32 v[30:31], v[60:61], v[30:31], v[26:27] op_sel_hi:[0,1,1]
	v_pk_fma_f32 v[34:35], v[60:61], v[54:55], v[34:35] op_sel_hi:[0,1,1]
	v_pk_fma_f32 v[32:33], v[60:61], v[32:33], v[28:29] op_sel_hi:[0,1,1]
	v_cvt_pk_bf16_f32 v74, v36, v37
	v_cvt_pk_bf16_f32 v75, v30, v31
	v_cvt_pk_bf16_f32 v76, v34, v35
	v_cvt_pk_bf16_f32 v77, v32, v33
	global_load_dword v44, v[24:25], off offset:96
	global_load_dword v45, v[50:51], off offset:96
	global_load_dword v46, v[52:53], off offset:96
	s_nop 0
	global_load_dwordx4 v[24:27], v[20:21], off offset:2048
	s_nop 0
	global_load_dwordx4 v[18:21], v[18:19], off offset:2048
	s_nop 0
	global_load_dwordx4 v[28:31], v[22:23], off offset:2048
	global_store_dwordx4 v[48:49], v[74:77], off offset:2048
	s_waitcnt vmcnt(4)
; __device__ __forceinline__ unsigned cvtpk(float lo, float hi) { f32x2_t v = {lo, hi}; bf16x2_t b = __builtin_convertvector(v, bf16x2_t); return __builtin_bit_cast(unsigned, b); }
; __global__ void __launch_bounds__(NTHREADS, 2) fwd_megakernel(Args args) {
;     ...
;         for (size_t it = gt; it < nitems; it += NGT) {
;             const size_t tok0 = (it >> 7) * TB; const int ac = (int)(it & 127), h = ac >> 4, c0 = ac * 8;
; #pragma unroll 4
;             for (int t = 0; t < TB; ++t) {
;                 const size_t tok = tok0 + t;
;                 const float l0 = LSE[tok * 8 + h], l1 = LSE[(size_t)MTOK * 8 + tok * 8 + h], l2 = LSE[(size_t)2 * MTOK * 8 + tok * 8 + h];
;                 const float mm = fmaxf(l0, fmaxf(l1, l2));
;                 float w0 = __builtin_amdgcn_exp2f(l0 - mm), w1 = __builtin_amdgcn_exp2f(l1 - mm), w2 = __builtin_amdgcn_exp2f(l2 - mm);
;                 const float inv = 1.0f / (w0 + w1 + w2); w0 *= inv; w1 *= inv; w2 *= inv;
;                 const v4u a0 = *(const v4u*)(OG0 + tok * 1024 + c0), a1 = *(const v4u*)(OG1 + tok * 1024 + c0), a2 = *(const v4u*)(OG2 + tok * 1024 + c0);
;                 v4u o;
;                 o.x = cvtpk(w0 * bflo(a0.x) + w1 * bflo(a1.x) + w2 * bflo(a2.x), w0 * bfhi(a0.x) + w1 * bfhi(a1.x) + w2 * bfhi(a2.x));
;                 o.y = cvtpk(w0 * bflo(a0.y) + w1 * bflo(a1.y) + w2 * bflo(a2.y), w0 * bfhi(a0.y) + w1 * bfhi(a1.y) + w2 * bfhi(a2.y));
;                 o.z = cvtpk(w0 * bflo(a0.z) + w1 * bflo(a1.z) + w2 * bflo(a2.z), w0 * bfhi(a0.z) + w1 * bfhi(a1.z) + w2 * bfhi(a2.z));
;                 o.w = cvtpk(w0 * bflo(a0.w) + w1 * bflo(a1.w) + w2 * bflo(a2.w), w0 * bfhi(a0.w) + w1 * bfhi(a1.w) + w2 * bfhi(a2.w));
;                 *(v4u*)(YMIX + tok * DM + CONVW + c0) = o;
;             }
	v_max3_f32 v47, v44, v45, v46
	s_waitcnt vmcnt(3)
	v_lshlrev_b32_e32 v22, 16, v24
	s_waitcnt vmcnt(2)
	v_and_b32_e32 v23, 0xffff0000, v18
	s_waitcnt vmcnt(1)
	v_lshlrev_b32_e32 v40, 16, v30
	v_and_b32_e32 v41, 0xffff0000, v30
	v_sub_f32_e32 v30, v44, v47
	v_sub_f32_e32 v44, v45, v47
	v_lshlrev_b32_e32 v32, 16, v18
	v_and_b32_e32 v33, 0xffff0000, v24
	v_lshlrev_b32_e32 v34, 16, v28
	v_and_b32_e32 v35, 0xffff0000, v28
	v_lshlrev_b32_e32 v36, 16, v25
	v_and_b32_e32 v37, 0xffff0000, v19
	v_lshlrev_b32_e32 v18, 16, v19
	v_and_b32_e32 v19, 0xffff0000, v25
	v_lshlrev_b32_e32 v24, 16, v29
	v_and_b32_e32 v25, 0xffff0000, v29
	v_lshlrev_b32_e32 v28, 16, v26
	v_and_b32_e32 v29, 0xffff0000, v20
	v_lshlrev_b32_e32 v38, 16, v20
	v_and_b32_e32 v39, 0xffff0000, v26
	v_lshlrev_b32_e32 v42, 16, v27
	v_and_b32_e32 v43, 0xffff0000, v21
	v_lshlrev_b32_e32 v20, 16, v21
	v_and_b32_e32 v21, 0xffff0000, v27
	v_lshlrev_b32_e32 v26, 16, v31
	v_and_b32_e32 v27, 0xffff0000, v31
	v_sub_f32_e32 v45, v46, v47
	v_exp_f32_e32 v31, v30
	v_exp_f32_e32 v30, v44
	v_exp_f32_e32 v46, v45
	v_add_f32_e32 v44, v31, v30
	v_add_f32_e32 v45, v46, v44
	v_div_scale_f32 v44, s[4:5], v45, v45, 1.0
	v_rcp_f32_e32 v48, v44
	v_div_scale_f32 v47, vcc, 1.0, v45, 1.0
	v_fma_f32 v49, -v44, v48, 1.0
	v_fmac_f32_e32 v48, v49, v48
	v_mul_f32_e32 v49, v47, v48
	v_fma_f32 v50, -v44, v49, v47
	v_fmac_f32_e32 v49, v50, v48
	v_fma_f32 v44, -v44, v49, v47
	v_div_fmas_f32 v47, v44, v48, v49
	v_add_co_u32_e32 v44, vcc, 0x3000, v16
	v_div_fixup_f32 v16, v47, v45, 1.0
	s_nop 0
	v_addc_co_u32_e32 v45, vcc, 0, v17, vcc
	v_mul_f32_e32 v46, v46, v16
	v_pk_mul_f32 v[16:17], v[30:31], v[16:17] op_sel_hi:[1,0]
	s_nop 0
	v_pk_mul_f32 v[30:31], v[16:17], v[32:33] op_sel:[1,0] op_sel_hi:[0,1]
	v_pk_mul_f32 v[18:19], v[16:17], v[18:19] op_sel:[1,0] op_sel_hi:[0,1]
	v_pk_mul_f32 v[32:33], v[16:17], v[38:39] op_sel:[1,0] op_sel_hi:[0,1]
	v_pk_mul_f32 v[20:21], v[16:17], v[20:21] op_sel:[1,0] op_sel_hi:[0,1]
	v_pk_fma_f32 v[22:23], v[16:17], v[22:23], v[30:31]
	v_pk_fma_f32 v[18:19], v[16:17], v[36:37], v[18:19]
	v_pk_fma_f32 v[28:29], v[16:17], v[28:29], v[32:33]
	v_pk_fma_f32 v[16:17], v[16:17], v[42:43], v[20:21]
	v_pk_fma_f32 v[20:21], v[46:47], v[34:35], v[22:23] op_sel_hi:[0,1,1]
	v_pk_fma_f32 v[18:19], v[46:47], v[24:25], v[18:19] op_sel_hi:[0,1,1]
	v_pk_fma_f32 v[22:23], v[46:47], v[40:41], v[28:29] op_sel_hi:[0,1,1]
	v_pk_fma_f32 v[24:25], v[46:47], v[26:27], v[16:17] op_sel_hi:[0,1,1]
	v_cvt_pk_bf16_f32 v16, v20, v21
	v_cvt_pk_bf16_f32 v17, v18, v19
	v_cvt_pk_bf16_f32 v18, v22, v23
	v_cvt_pk_bf16_f32 v19, v24, v25
	global_store_dwordx4 v[44:45], v[16:19], off offset:2048
	s_cbranch_scc0 .LBB0_209
	v_lshl_add_u64 v[8:9], v[8:9], 0, s[24:25]
	v_cmp_lt_u64_e32 vcc, s[60:61], v[8:9]
	s_or_b64 s[8:9], vcc, s[8:9]
	s_andn2_b64 exec, exec, s[8:9]
	s_cbranch_execnz .LBB0_208

; #define PG8_STAGE(bufoff, gbase, voff) do { _Pragma("unroll") for (int _i = 0; _i < 2; ++_i) \
;         __builtin_amdgcn_global_load_lds((const unsigned*)((const char*)(gbase) + (voff)[_i]), (PG8_LAS unsigned*)(lds + (bufoff) + ldsw + _i * 8192), 16, 0, 0); } while (0)
; #define PG8_WAIT_V(n) asm volatile("s_waitcnt vmcnt(" #n ")" ::: "memory")
; #define PG8_BAR __builtin_amdgcn_s_barrier()
; template <class Epi, class Sched, bool ALIGN_EPI = false, bool SP2 = false>
; __device__ __forceinline__ void gemm_phase(PG8_LAS unsigned char* lds, const Gemm g, const Sched& S, const Epi& E) {
;     ...
;     for (int i = 0; i < 2; ++i) { int R, C; stage_rc(tid * 16 + i * 8192, R, C); const int Rb = Epi::PERM ? ((R & ~31) + perm32(R & 31)) : R;
;         voffA[i] = (unsigned)(R * K + C) * 2u; voffB[i] = (unsigned)(Rb * K + C) * 2u; }
;     ...
;     const char* cA = (const char*)g.A + (size_t)cur.pm * tstep; const char* cB = (const char*)g.Bt + (size_t)cur.pn * tstep;
;     S.a_ready(cur);
;     if constexpr (SP2) {
;         PG8_STAGE(PG8_SB(0, 0), cB, voffB); PG8_STAGE(PG8_SB(0, 1), cB + hstep, voffB); PG8_STAGE(PG8_SA(0, 0), cA, voffA); PG8_STAGE(PG8_SA(0, 1), cA + hstep, voffA);
;         if (wr == 1) PG8_BAR;
;         PG8_WAIT_V(2); PG8_BAR;
;         PG8_STAGE(PG8_SB(1, 0), cB + kstep, voffB); PG8_STAGE(PG8_SA(1, 0), cA + kstep, voffA); PG8_STAGE(PG8_SB(1, 1), cB + hstep + kstep, voffB);
.LBB0_395:
	s_or_b64 exec, exec, s[4:5]
	s_add_u32 s12, s40, 0x27c00000
	s_addc_u32 s13, s41, 0
	s_add_u32 s20, s40, 0x3dc00000
	s_addc_u32 s21, s41, 0
	v_mov_b32_e32 v11, v178
	s_waitcnt lgkmcnt(0)
	s_barrier
	s_cmpk_gt_i32 s2, 0x15ff
	v_readfirstlane_b32 s1, v11
	s_cbranch_scc1 .LBB0_420
	v_lshlrev_b32_e32 v0, 4, v11
	v_add_u32_e32 v1, 0x2000, v0
	v_ashrrev_i32_e32 v2, 31, v1
	v_lshrrev_b32_e32 v2, 22, v2
	v_add_u32_e32 v2, v1, v2
	v_ashrrev_i32_e32 v8, 10, v2
	v_mul_i32_i24_e32 v2, 0x400, v8
	v_sub_u32_e32 v1, v1, v2
	v_lshrrev_b32_e32 v2, 4, v1
	v_bitop3_b32 v1, v2, v1, 32 bitop3:0x6c
	v_ashrrev_i32_e32 v2, 31, v1
	v_lshrrev_b32_e32 v2, 26, v2
	v_add_u32_e32 v2, v1, v2
	v_lshlrev_b32_e32 v3, 3, v8
	v_ashrrev_i32_e32 v9, 6, v2
	v_and_b32_e32 v3, -16, v3
	v_add_u32_e32 v3, v9, v3
	v_and_b32_e32 v4, 3, v9
	s_mov_b32 s4, 0xfffe0
	v_lshrrev_b32_e32 v5, 2, v3
	v_lshlrev_b32_e32 v6, 1, v3
	v_and_b32_e32 v2, 0xc0, v2
	v_and_or_b32 v4, v3, s4, v4
	v_and_b32_e32 v5, 4, v5
	v_and_b32_e32 v6, 24, v6
	v_sub_u32_e32 v1, v1, v2
	v_mov_b32_e32 v2, 1
	v_or3_b32 v4, v4, v5, v6
	v_lshlrev_b32_e32 v5, 5, v8
	v_ashrrev_i16_sdwa v1, v2, sext(v1) dst_sel:DWORD dst_unused:UNUSED_PAD src0_sel:DWORD src1_sel:BYTE_0
	v_and_b32_e32 v5, 32, v5
	v_bfe_i32 v10, v1, 0, 16
	v_add_lshl_u32 v1, v5, v10, 1
	v_lshl_add_u32 v180, v4, 12, v1
	v_bfe_u32 v15, v3, 4, 2
	v_and_b32_e32 v16, 15, v3
	v_lshl_or_b32 v15, v16, 2, v15
	v_and_or_b32 v15, v3, 64, v15
	v_lshl_add_u32 v182, v15, 12, v1
	v_bfe_i32 v1, v11, 27, 1
	v_lshrrev_b32_e32 v1, 22, v1
	v_add_u32_e32 v1, v0, v1
	v_and_b32_e32 v1, 0xfffffc00, v1
	v_sub_u32_e32 v0, v0, v1
	v_lshrrev_b32_e32 v1, 4, v0
	v_ashrrev_i32_e32 v3, 31, v11
	v_bitop3_b32 v0, v1, v0, 32 bitop3:0x6c
	v_lshrrev_b32_e32 v3, 26, v3
	v_ashrrev_i32_e32 v1, 31, v0
	v_add_u32_e32 v3, v11, v3
	v_lshrrev_b32_e32 v1, 26, v1
	v_ashrrev_i32_e32 v13, 6, v3
	v_add_u32_e32 v1, v0, v1
	v_lshlrev_b32_e32 v3, 3, v13
	v_ashrrev_i32_e32 v12, 6, v1
	v_and_b32_e32 v3, -16, v3
	v_add_u32_e32 v3, v12, v3
	v_and_b32_e32 v4, 3, v12
	v_and_or_b32 v4, v3, s4, v4
	s_lshr_b32 s4, s3, 29
	s_add_i32 s4, s2, s4
	s_ashr_i32 s0, s1, 6
	s_ashr_i32 s5, s4, 3
	s_and_b32 s4, s4, -8
	s_ashr_i32 s6, s1, 8
	s_lshl_b32 s29, s0, 10
	s_sub_i32 s4, s2, s4
	s_cmp_lt_i32 s4, 0
	s_movk_i32 s76, 0x2c1
	s_cselect_b32 s7, s76, 0x2c0
	s_mul_i32 s4, s4, s7
	s_add_i32 s4, s4, s5
	s_mul_hi_i32 s5, s4, 0x2e8ba2e9
	s_lshr_b32 s7, s5, 31
	s_ashr_i32 s5, s5, 6
	s_add_i32 s5, s5, s7
	s_lshl_b32 s7, s5, 3
	s_mulk_i32 s5, 0x160
	s_sub_i32 s5, s4, s5
	s_sext_i32_i16 s4, s5
	s_bfe_u32 s4, s4, 0x3001c
	s_add_i32 s8, s5, s4
	s_sext_i32_i16 s4, s8
	s_and_b32 s8, s8, 0xfff8
	s_sub_i32 s5, s5, s8
	s_sext_i32_i16 s5, s5
	v_lshrrev_b32_e32 v5, 2, v3
	v_lshlrev_b32_e32 v6, 1, v3
	v_and_b32_e32 v1, 0xc0, v1
	s_lshr_b32 s4, s4, 3
	s_add_i32 s70, s7, s5
	v_and_b32_e32 v5, 4, v5
	v_and_b32_e32 v6, 24, v6
	v_sub_u32_e32 v0, v0, v1
	s_ashr_i32 s71, s70, 31
	s_bfe_i64 s[10:11], s[4:5], 0x100000
	v_or3_b32 v4, v4, v5, v6
	v_lshlrev_b32_e32 v5, 5, v13
	v_ashrrev_i16_sdwa v0, v2, sext(v0) dst_sel:DWORD dst_unused:UNUSED_PAD src0_sel:DWORD src1_sel:BYTE_0
	s_lshl_b64 s[8:9], s[70:71], 20
	s_lshl_b64 s[10:11], s[10:11], 20
	v_and_b32_e32 v5, 32, v5
	v_bfe_i32 v14, v0, 0, 16
	s_add_u32 s72, s34, s10
	v_add_lshl_u32 v0, v5, v14, 1
	s_addc_u32 s73, s35, s11
	s_add_i32 s77, s29, 0
	v_lshl_add_u32 v184, v4, 12, v0
	s_add_i32 m0, s77, 0x10000
	v_bfe_u32 v15, v3, 4, 2
	v_and_b32_e32 v16, 15, v3
	v_lshl_or_b32 v15, v16, 2, v15
	v_and_or_b32 v15, v3, 64, v15
	v_lshl_add_u32 v186, v15, 12, v0
	global_load_lds_dwordx4 v184, s[72:73]
	s_add_i32 m0, s77, 0x12000
	s_add_u32 s10, s72, 0x80000
	global_load_lds_dwordx4 v180, s[72:73]
	s_addc_u32 s11, s73, 0
	s_add_i32 m0, s77, 0x14000
	v_mov_b32_e32 v189, 0
	global_load_lds_dwordx4 v184, s[10:11]
	s_add_i32 m0, s77, 0x16000
	v_mov_b32_e32 v185, v189
	global_load_lds_dwordx4 v180, s[10:11]
	s_add_u32 s10, s90, s8
	s_addc_u32 s11, s91, s9
	s_add_i32 s78, s77, 0x2000
	s_mov_b32 m0, s77
	s_add_u32 s8, s10, 0x80000
	global_load_lds_dwordx4 v186, s[10:11]
	s_mov_b32 m0, s78
	s_addc_u32 s9, s11, 0
	s_add_i32 s79, s77, 0x4000
	global_load_lds_dwordx4 v182, s[10:11]
	s_mov_b32 m0, s79
	s_add_i32 s80, s77, 0x6000
	global_load_lds_dwordx4 v186, s[8:9]
	s_mov_b32 m0, s80
	v_mov_b32_e32 v181, v189
	global_load_lds_dwordx4 v182, s[8:9]
	v_mov_b32_e32 v187, v189
	v_mov_b32_e32 v183, v189
	s_cmp_eq_u32 s6, 1
	s_mov_b32 s23, 0
	v_lshl_add_u64 v[6:7], s[72:73], 0, v[184:185]
	v_lshl_add_u64 v[4:5], s[72:73], 0, v[180:181]
	v_lshl_add_u64 v[0:1], s[10:11], 0, v[186:187]
	s_cselect_b64 s[36:37], -1, 0
	s_cmp_lg_u32 s6, 1
	v_lshl_add_u64 v[2:3], s[10:11], 0, v[182:183]
	s_cbranch_scc1 .LBB0_398
	s_barrier
; #define PG8_STAGE(bufoff, gbase, voff) do { _Pragma("unroll") for (int _i = 0; _i < 2; ++_i) \
;         __builtin_amdgcn_global_load_lds((const unsigned*)((const char*)(gbase) + (voff)[_i]), (PG8_LAS unsigned*)(lds + (bufoff) + ldsw + _i * 8192), 16, 0, 0); } while (0)
; #define PG8_WAIT_V(n) asm volatile("s_waitcnt vmcnt(" #n ")" ::: "memory")
; #define PG8_BAR __builtin_amdgcn_s_barrier()
; template <class Epi, class Sched, bool ALIGN_EPI = false, bool SP2 = false>
; __device__ __forceinline__ void gemm_phase(PG8_LAS unsigned char* lds, const Gemm g, const Sched& S, const Epi& E) {
;     ...
;     for (int i = 0; i < 2; ++i) { int R, C; stage_rc(tid * 16 + i * 8192, R, C); const int Rb = Epi::PERM ? ((R & ~31) + perm32(R & 31)) : R;
;         voffA[i] = (unsigned)(R * K + C) * 2u; voffB[i] = (unsigned)(Rb * K + C) * 2u; }
;     ...
;         PG8_STAGE(PG8_SB(1, 0), cB + kstep, voffB); PG8_STAGE(PG8_SA(1, 0), cA + kstep, voffA); PG8_STAGE(PG8_SB(1, 1), cB + hstep + kstep, voffB);
;         PG8_WAIT_V(6); PG8_BAR;
.LBB0_398:
	s_mov_b64 s[52:53], 0x80
	s_and_b32 s81, s0, 3
	s_add_i32 m0, s77, 0x18000
	v_lshl_add_u64 v[6:7], v[6:7], 0, s[52:53]
	s_lshl_b32 s5, s6, 13
	s_lshl_b32 s82, s81, 5
	s_lshl_b32 s7, s81, 12
	s_waitcnt vmcnt(2)
	s_barrier
	global_load_lds_dwordx4 v[6:7], off
	v_lshl_add_u64 v[4:5], v[4:5], 0, s[52:53]
	s_add_i32 m0, s77, 0x1a000
	s_add_i32 s83, s77, 0x8000
	s_add_i32 s84, s77, 0xa000
	global_load_lds_dwordx4 v[4:5], off
	v_lshl_add_u64 v[0:1], v[0:1], 0, s[52:53]
	s_mov_b32 m0, s83
	s_add_u32 s8, s72, 0x80080
	global_load_lds_dwordx4 v[0:1], off
	v_lshl_add_u64 v[0:1], v[2:3], 0, s[52:53]
	s_mov_b32 m0, s84
	s_addc_u32 s9, s73, 0
	global_load_lds_dwordx4 v[0:1], off
	s_add_i32 m0, s77, 0x1c000
	v_lshl_add_u64 v[0:1], s[8:9], 0, v[184:185]
	global_load_lds_dwordx4 v[0:1], off
	v_lshl_add_u64 v[0:1], s[8:9], 0, v[180:181]
	s_add_i32 m0, s77, 0x1e000
	s_cmpk_lt_u32 s1, 0x100
	global_load_lds_dwordx4 v[0:1], off
	v_lshlrev_b32_e32 v5, 15, v13
	v_and_b32_e32 v190, 15, v11
	s_cselect_b64 s[54:55], -1, 0
	s_lshl_b32 s8, s81, 9
	s_add_i32 s9, 0, 0x20400
	v_and_b32_e32 v5, 0xffff0000, v5
	s_lshl_b32 s1, s6, 11
	v_cmp_gt_u32_e32 vcc, 2, v190
	s_add_i32 s8, s9, s8
	v_lshl_add_u32 v5, v12, 12, v5
	v_and_b32_e32 v6, 1, v13
	s_and_b64 s[56:57], s[54:55], vcc
	s_add_i32 s1, s8, s1
	v_lshl_or_b32 v5, v6, 6, v5
	v_bfe_u32 v0, v11, 4, 2
	s_add_u32 s58, s26, 0xb000
	v_lshl_add_u32 v196, v14, 1, v5
	v_lshlrev_b32_e32 v5, 15, v8
	v_lshlrev_b32_e32 v212, 4, v0
	v_lshlrev_b32_e32 v1, 2, v11
	v_mov_b32_e32 v191, v189
	s_addc_u32 s59, s27, 0
	v_and_b32_e32 v5, 0xffff0000, v5
	v_lshlrev_b32_e32 v192, 3, v0
	v_lshl_or_b32 v0, v190, 6, v212
	v_and_b32_e32 v1, 32, v1
	s_waitcnt vmcnt(6)
	v_lshl_add_u64 v[194:195], v[190:191], 0, -12
	v_lshl_add_u32 v191, v190, 8, s1
	s_add_u32 s60, s26, 0x16000
	v_lshl_add_u32 v5, v9, 12, v5
	v_and_b32_e32 v6, 1, v8
	v_bitop3_b32 v2, v0, s5, v1 bitop3:0xde
	v_bitop3_b32 v213, v0, s7, v1 bitop3:0xde
	v_add_u32_e32 v0, 0xfffff200, v191
	v_add_u32_e32 v1, 0xfffff240, v191
	v_add_u32_e32 v3, 0xfffff280, v191
	v_add_u32_e32 v4, 0xfffff2c0, v191
	s_addc_u32 s61, s27, 0
	v_lshl_or_b32 v5, v6, 6, v5
	s_add_i32 s85, 0, 0x10000
	s_add_i32 s86, 0, 0x14000
	s_sext_i32_i16 s0, s4
	v_lshl_or_b32 v193, s6, 6, v190
	v_cmp_lt_u32_e64 s[4:5], 13, v190
	v_cmp_eq_u32_e64 s[6:7], 0, v190
	v_add_u32_e32 v214, s8, v212
	v_or_b32_e32 v215, s82, v192
	v_add_u32_e32 v216, s9, v212
	v_mov_b32_e32 v197, v189
	v_lshl_add_u32 v198, v10, 1, v5
	v_mov_b32_e32 v196, v186
	v_mov_b32_e32 v198, v182
	v_mov_b32_e32 v199, v189
	v_mov_b64_e32 v[200:201], 0x1600
	v_mov_b64_e32 v[202:203], 0x15ff
	v_add_u32_e32 v217, s85, v213
	v_add_u32_e32 v218, s86, v213
	v_add_u32_e32 v219, 0, v2
	v_add_u32_e32 v220, v0, v212
	v_add_u32_e32 v221, v1, v212
	v_add_u32_e32 v222, v3, v212
	v_add_u32_e32 v223, v4, v212
	s_mov_b32 s87, 0xb000
	s_movk_i32 s92, 0x5000
	s_movk_i32 s93, 0x2c00
	v_mov_b32_e32 v224, 0xb000
	s_mov_b32 s94, 0
	s_barrier
	s_branch .LBB0_401

; #define PG8_LAS __attribute__((address_space(3)))
;     __device__ __forceinline__ void operator()(const f32x4 (&acc)[2][2][4][2], const Unit& u, int wr, int wc, int fr, int fq) const {
;     ...
;         if (fr >= 14) {
; #pragma unroll
;             for (int ai = 0; ai < 2; ++ai)
; #pragma unroll
;                 for (int bj = 0; bj < 2; ++bj)
; #pragma unroll
;                     for (int n = 0; n < 2; ++n) *(PG8_LAS f32x4*)(xch + ((ai * 2 + wr) * 4 + wc) * 128 + (fr - 14) * 64 + (bj * 2 + n) * 16 + fq * 4) = acc[ai][bj][3][n];
;             if (wr == 1) {
; #pragma unroll
;                 for (int bj = 0; bj < 2; ++bj)
; #pragma unroll
;                     for (int n = 0; n < 2; ++n) *(f32x4*)(raw + ((size_t)u.pm * 4 + 2 + (fr - 14)) * upw + u.pn * BM + bj * HALF + wc * 32 + 8 * fq + 4 * n) = acc[1][bj][3][n];
;             }
;         }
;         if (fr < 2 && wr == 0) {
; #pragma unroll
;             for (int bj = 0; bj < 2; ++bj)
; #pragma unroll
;                 for (int n = 0; n < 2; ++n) *(f32x4*)(raw + ((size_t)u.pm * 4 + fr) * upw + u.pn * BM + bj * HALF + wc * 32 + 8 * fq + 4 * n) = acc[0][bj][0][n];
;         }
;         asm volatile("s_waitcnt lgkmcnt(0)" ::: "memory"); __builtin_amdgcn_s_barrier(); asm volatile("" ::: "memory");
;         u32x2 keep[2][4];
; #pragma unroll
;         for (int n = 0; n < 2; ++n) {
;             const int ch0 = u.pn * HALF + wc * 32 + 8 * fq + 4 * n;
;             f32x4 w0[2], w1[2], w2[2], bb[2];
; #pragma unroll
;             for (int bj = 0; bj < 2; ++bj) { w0[bj] = *(const f32x4*)(cw + bj * dff + ch0); w1[bj] = *(const f32x4*)(cw + upw + bj * dff + ch0); w2[bj] = *(const f32x4*)(cw + 2 * upw + bj * dff + ch0); bb[bj] = *(const f32x4*)(cb + bj * dff + ch0); }
.LBB0_407:
	v_cmp_eq_u32_e64 s[10:11], 15, v190
	v_add_u32_e32 v205, v212, v191
	v_add_u32_e32 v205, 0xfffff100, v205
	s_mul_i32 s1, s70, 0x2c000
	s_lshl_b32 s22, s0, 10
	s_add_i32 s1, s1, s22
	s_lshl_b32 s22, s81, 7
	s_add_i32 s1, s1, s22
	s_add_u32 s46, s20, s1
	s_addc_u32 s47, s21, 0
	v_lshl_add_u32 v204, v192, 2, 0
	s_and_saveexec_b64 s[72:73], s[10:11]
	s_cbranch_execz .Lffn_a1
	ds_write_b128 v205, v[108:111]
	ds_write_b128 v205, v[44:47] offset:64
	ds_write_b128 v205, v[100:103] offset:128
	ds_write_b128 v205, v[36:39] offset:192
	ds_write_b128 v205, v[104:107] offset:256
	ds_write_b128 v205, v[40:43] offset:320
	ds_write_b128 v205, v[96:99] offset:384
	ds_write_b128 v205, v[32:35] offset:448
	ds_write_b128 v205, v[76:79] offset:4096
	ds_write_b128 v205, v[12:15] offset:4160
	ds_write_b128 v205, v[68:71] offset:4224
	ds_write_b128 v205, v[4:7] offset:4288
	ds_write_b128 v205, v[72:75] offset:4352
	ds_write_b128 v205, v[8:11] offset:4416
	ds_write_b128 v205, v[64:67] offset:4480
	ds_write_b128 v205, v[0:3] offset:4544
	s_and_b64 vcc, exec, s[36:37]
	s_cbranch_vccz .Lffn_a1
	s_add_u32 s46, s46, 0x16000
	s_addc_u32 s47, s47, 0
	global_store_dwordx4 v204, v[76:79], s[46:47]
	global_store_dwordx4 v204, v[12:15], s[46:47] offset:16
	global_store_dwordx4 v204, v[68:71], s[46:47] offset:512
	global_store_dwordx4 v204, v[4:7], s[46:47] offset:528
	s_add_u32 s46, s46, 0xb000
	s_addc_u32 s47, s47, 0
	global_store_dwordx4 v204, v[72:75], s[46:47]
	global_store_dwordx4 v204, v[8:11], s[46:47] offset:16
	global_store_dwordx4 v204, v[64:67], s[46:47] offset:512
	global_store_dwordx4 v204, v[0:3], s[46:47] offset:528
.Lffn_a1:
	s_or_b64 exec, exec, s[72:73]
	s_and_b64 s[10:11], s[6:7], s[54:55]
	s_and_saveexec_b64 s[72:73], s[10:11]
	s_cbranch_execz .Lffn_a2
	global_store_dwordx4 v204, v[162:165], s[46:47]
	global_store_dwordx4 v204, v[60:63], s[46:47] offset:16
	global_store_dwordx4 v204, v[158:161], s[46:47] offset:512
	global_store_dwordx4 v204, v[56:59], s[46:47] offset:528
	s_add_u32 s46, s46, 0xb000
	s_addc_u32 s47, s47, 0
	global_store_dwordx4 v204, v[122:125], s[46:47]
	global_store_dwordx4 v204, v[52:55], s[46:47] offset:16
	global_store_dwordx4 v204, v[114:117], s[46:47] offset:512
	global_store_dwordx4 v204, v[48:51], s[46:47] offset:528
.Lffn_a2:
	s_or_b64 exec, exec, s[72:73]
	s_lshl_b32 s1, s0, 9
	s_lshl_b32 s22, s81, 7
	s_add_i32 s1, s1, s22
	v_lshl_add_u32 v112, v192, 2, s1
	v_add_u32_e32 v113, 0x5800, v112
	s_mul_i32 s1, s70, 0x2c0000
	s_lshl_b32 s22, s0, 8
	s_add_i32 s1, s1, s22
	s_lshl_b32 s22, s81, 6
	s_add_i32 s1, s1, s22
	s_add_u32 s30, s12, s1
	s_addc_u32 s31, s13, 0
	s_and_b64 vcc, exec, s[36:37]
	s_cbranch_vccz .Lffn_b0
	s_add_u32 s30, s30, 0xb0000
	s_addc_u32 s31, s31, 0
.Lffn_b0:
	v_mul_u32_u24_e32 v188, 0xb000, v190
	v_add_u32_e32 v188, v212, v188
	s_mov_b32 s71, 0xbfb8aa3b
	s_waitcnt lgkmcnt(0)
	s_barrier
	global_load_dwordx4 v[126:129], v112, s[26:27]
	global_load_dwordx4 v[130:133], v113, s[26:27]
	global_load_dwordx4 v[134:137], v112, s[58:59]
	global_load_dwordx4 v[138:141], v113, s[58:59]
	global_load_dwordx4 v[142:145], v112, s[60:61]
	global_load_dwordx4 v[146:149], v113, s[60:61]
	global_load_dwordx4 v[150:153], v112, s[44:45]
	global_load_dwordx4 v[154:157], v113, s[44:45]
	v_mov_b32_e32 v166, 0
	v_mov_b32_e32 v174, 0
	v_mov_b32_e32 v167, 0
	v_mov_b32_e32 v175, 0
	v_mov_b32_e32 v168, 0
	v_mov_b32_e32 v176, 0
	v_mov_b32_e32 v169, 0
	v_mov_b32_e32 v177, 0
	v_mov_b32_e32 v170, 0
	v_mov_b32_e32 v118, 0
	v_mov_b32_e32 v171, 0
	v_mov_b32_e32 v119, 0
	v_mov_b32_e32 v172, 0
	v_mov_b32_e32 v120, 0
	v_mov_b32_e32 v173, 0
	v_mov_b32_e32 v121, 0
	s_and_b64 vcc, exec, s[36:37]
	s_cbranch_vccz .Lffn_h00
	ds_read_b128 v[166:169], v214
	ds_read_b128 v[174:177], v214 offset:256
	ds_read_b128 v[170:173], v214 offset:128
	ds_read_b128 v[118:121], v214 offset:384
.Lffn_h00:
	s_waitcnt vmcnt(0) lgkmcnt(0)
	v_mov_b32_dpp v174, v104 row_shr:1 row_mask:0xf bank_mask:0xf
	v_mov_b32_dpp v175, v105 row_shr:1 row_mask:0xf bank_mask:0xf
	v_mov_b32_dpp v176, v106 row_shr:1 row_mask:0xf bank_mask:0xf
	v_mov_b32_dpp v177, v107 row_shr:1 row_mask:0xf bank_mask:0xf
	v_mov_b32_dpp v166, v108 row_shr:1 row_mask:0xf bank_mask:0xf
	v_mov_b32_dpp v167, v109 row_shr:1 row_mask:0xf bank_mask:0xf
	v_mov_b32_dpp v168, v110 row_shr:1 row_mask:0xf bank_mask:0xf
	v_mov_b32_dpp v169, v111 row_shr:1 row_mask:0xf bank_mask:0xf
	v_fma_f32 v104, v142, v104, v150
	v_fma_f32 v105, v143, v105, v151
	v_fma_f32 v106, v144, v106, v152
	v_fma_f32 v107, v145, v107, v153
	v_fmac_f32_e32 v104, v134, v108
	v_fmac_f32_e32 v105, v135, v109
	v_fmac_f32_e32 v106, v136, v110
	v_fmac_f32_e32 v107, v137, v111
	v_fmac_f32_e32 v104, v126, v122
	v_fmac_f32_e32 v105, v127, v123
	v_fmac_f32_e32 v106, v128, v124
	v_fmac_f32_e32 v107, v129, v125
	v_fma_f32 v108, v142, v108, v150
	v_fma_f32 v109, v143, v109, v151
	v_fma_f32 v110, v144, v110, v152
	v_fma_f32 v111, v145, v111, v153
	v_fmac_f32_e32 v108, v134, v122
	v_fmac_f32_e32 v109, v135, v123
	v_fmac_f32_e32 v110, v136, v124
	v_fmac_f32_e32 v111, v137, v125
	v_fmac_f32_e32 v108, v126, v162
	v_fmac_f32_e32 v109, v127, v163
	v_fmac_f32_e32 v110, v128, v164
	v_fmac_f32_e32 v111, v129, v165
	v_fma_f32 v122, v142, v122, v150
	v_fma_f32 v123, v143, v123, v151
	v_fma_f32 v124, v144, v124, v152
	v_fma_f32 v125, v145, v125, v153
	v_fmac_f32_e32 v122, v134, v162
	v_fmac_f32_e32 v123, v135, v163
	v_fmac_f32_e32 v124, v136, v164
	v_fmac_f32_e32 v125, v137, v165
	v_fmac_f32_e32 v122, v126, v174
	v_fmac_f32_e32 v123, v127, v175
	v_fmac_f32_e32 v124, v128, v176
	v_fmac_f32_e32 v125, v129, v177
	v_fma_f32 v162, v142, v162, v150
	v_fma_f32 v163, v143, v163, v151
; __device__ __forceinline__ unsigned cvt_pk_bf16(float lo, float hi) { unsigned r; asm volatile("v_cvt_pk_bf16_f32 %0, %1, %2" : "=v"(r) : "v"(lo), "v"(hi)); return r; }
;     __device__ __forceinline__ void operator()(const f32x4 (&acc)[2][2][4][2], const Unit& u, int wr, int wc, int fr, int fq) const {
;     ...
;                             const float cur = acc[ai][bj][m][n][jj];
;                             float o1, o2;
;                             if (m > 0) { const float pv = acc[ai][bj][m > 0 ? m - 1 : 0][n][jj]; o1 = dppf<0x121>(0.f, pv); o2 = dppf<0x122>(0.f, pv); }
;                             else { o1 = h15[bj][jj]; o2 = (fr == 0) ? h14[bj][jj] : h15[bj][jj]; }
;                             const float p1 = dppf<0x111>(o1, cur), p2 = dppf<0x112>(o2, cur);
;                             val[bj][jj] = w2[bj][jj] * cur + w1[bj][jj] * p1 + w0[bj][jj] * p2 + bb[bj][jj];
;                         }
;                     float y[4];
; #pragma unroll
;                     for (int jj = 0; jj < 4; ++jj) { const float g = val[1][jj]; y[jj] = val[0][jj] * g * __builtin_amdgcn_rcpf(1.0f + __builtin_amdgcn_exp2f(-1.4426950408889634f * g)); }
;                     u32x2 w; w.x = cvt_pk_bf16(y[0], y[1]); w.y = cvt_pk_bf16(y[2], y[3]);
	v_fma_f32 v164, v144, v164, v152
	v_fma_f32 v165, v145, v165, v153
	v_fmac_f32_e32 v162, v134, v174
	v_fmac_f32_e32 v163, v135, v175
	v_fmac_f32_e32 v164, v136, v176
	v_fmac_f32_e32 v165, v137, v177
	v_fmac_f32_e32 v162, v126, v166
	v_fmac_f32_e32 v163, v127, v167
	v_fmac_f32_e32 v164, v128, v168
	v_fmac_f32_e32 v165, v129, v169
	v_mov_b32_dpp v118, v96 row_shr:1 row_mask:0xf bank_mask:0xf
	v_mov_b32_dpp v119, v97 row_shr:1 row_mask:0xf bank_mask:0xf
	v_mov_b32_dpp v120, v98 row_shr:1 row_mask:0xf bank_mask:0xf
	v_mov_b32_dpp v121, v99 row_shr:1 row_mask:0xf bank_mask:0xf
	v_mov_b32_dpp v170, v100 row_shr:1 row_mask:0xf bank_mask:0xf
	v_mov_b32_dpp v171, v101 row_shr:1 row_mask:0xf bank_mask:0xf
	v_mov_b32_dpp v172, v102 row_shr:1 row_mask:0xf bank_mask:0xf
	v_mov_b32_dpp v173, v103 row_shr:1 row_mask:0xf bank_mask:0xf
	v_fma_f32 v96, v146, v96, v154
	v_fma_f32 v97, v147, v97, v155
	v_fma_f32 v98, v148, v98, v156
	v_fma_f32 v99, v149, v99, v157
	v_fmac_f32_e32 v96, v138, v100
	v_fmac_f32_e32 v97, v139, v101
	v_fmac_f32_e32 v98, v140, v102
	v_fmac_f32_e32 v99, v141, v103
	v_fmac_f32_e32 v96, v130, v114
	v_fmac_f32_e32 v97, v131, v115
	v_fmac_f32_e32 v98, v132, v116
	v_fmac_f32_e32 v99, v133, v117
	v_fma_f32 v100, v146, v100, v154
	v_fma_f32 v101, v147, v101, v155
	v_fma_f32 v102, v148, v102, v156
	v_fma_f32 v103, v149, v103, v157
	v_fmac_f32_e32 v100, v138, v114
	v_fmac_f32_e32 v101, v139, v115
	v_fmac_f32_e32 v102, v140, v116
	v_fmac_f32_e32 v103, v141, v117
	v_fmac_f32_e32 v100, v130, v158
	v_fmac_f32_e32 v101, v131, v159
	v_fmac_f32_e32 v102, v132, v160
	v_fmac_f32_e32 v103, v133, v161
	v_fma_f32 v114, v146, v114, v154
	v_fma_f32 v115, v147, v115, v155
	v_fma_f32 v116, v148, v116, v156
	v_fma_f32 v117, v149, v117, v157
	v_fmac_f32_e32 v114, v138, v158
	v_fmac_f32_e32 v115, v139, v159
	v_fmac_f32_e32 v116, v140, v160
	v_fmac_f32_e32 v117, v141, v161
	v_fmac_f32_e32 v114, v130, v118
	v_fmac_f32_e32 v115, v131, v119
	v_fmac_f32_e32 v116, v132, v120
	v_fmac_f32_e32 v117, v133, v121
	v_fma_f32 v158, v146, v158, v154
	v_fma_f32 v159, v147, v159, v155
	v_fma_f32 v160, v148, v160, v156
	v_fma_f32 v161, v149, v161, v157
	v_fmac_f32_e32 v158, v138, v118
	v_fmac_f32_e32 v159, v139, v119
	v_fmac_f32_e32 v160, v140, v120
	v_fmac_f32_e32 v161, v141, v121
	v_fmac_f32_e32 v158, v130, v170
	v_fmac_f32_e32 v159, v131, v171
	v_fmac_f32_e32 v160, v132, v172
	v_fmac_f32_e32 v161, v133, v173
	v_mul_f32_e32 v207, s71, v158
	v_mul_f32_e32 v208, s71, v159
	v_mul_f32_e32 v209, s71, v160
	v_mul_f32_e32 v210, s71, v161
	v_exp_f32_e32 v207, v207
	v_exp_f32_e32 v208, v208
	v_exp_f32_e32 v209, v209
	v_exp_f32_e32 v210, v210
	v_mul_f32_e32 v162, v162, v158
	v_mul_f32_e32 v163, v163, v159
	v_mul_f32_e32 v164, v164, v160
	v_mul_f32_e32 v165, v165, v161
	v_add_f32_e32 v207, 1.0, v207
	v_add_f32_e32 v208, 1.0, v208
	v_add_f32_e32 v209, 1.0, v209
	v_add_f32_e32 v210, 1.0, v210
	v_rcp_f32_e32 v207, v207
	v_rcp_f32_e32 v208, v208
	v_rcp_f32_e32 v209, v209
	v_rcp_f32_e32 v210, v210
	s_nop 0
	v_mul_f32_e32 v162, v162, v207
	v_mul_f32_e32 v163, v163, v208
	v_mul_f32_e32 v164, v164, v209
	v_mul_f32_e32 v165, v165, v210
	v_cvt_pk_bf16_f32 v158, v162, v163
	v_cvt_pk_bf16_f32 v159, v164, v165
	v_mul_f32_e32 v207, s71, v114
	v_mul_f32_e32 v208, s71, v115
	v_mul_f32_e32 v209, s71, v116
	v_mul_f32_e32 v210, s71, v117
	v_exp_f32_e32 v207, v207
	v_exp_f32_e32 v208, v208
	v_exp_f32_e32 v209, v209
	v_exp_f32_e32 v210, v210
	v_mul_f32_e32 v122, v122, v114
	v_mul_f32_e32 v123, v123, v115
	v_mul_f32_e32 v124, v124, v116
	v_mul_f32_e32 v125, v125, v117
	v_add_f32_e32 v207, 1.0, v207
	v_add_f32_e32 v208, 1.0, v208
	v_add_f32_e32 v209, 1.0, v209
	v_add_f32_e32 v210, 1.0, v210
	v_rcp_f32_e32 v207, v207
	v_rcp_f32_e32 v208, v208
	v_rcp_f32_e32 v209, v209
	v_rcp_f32_e32 v210, v210
	s_nop 0
	v_mul_f32_e32 v122, v122, v207
	v_mul_f32_e32 v123, v123, v208
	v_mul_f32_e32 v124, v124, v209
	v_mul_f32_e32 v125, v125, v210
	v_cvt_pk_bf16_f32 v114, v122, v123
	v_cvt_pk_bf16_f32 v115, v124, v125
	v_mul_f32_e32 v207, s71, v100
	v_mul_f32_e32 v208, s71, v101
	v_mul_f32_e32 v209, s71, v102
	v_mul_f32_e32 v210, s71, v103
	v_exp_f32_e32 v207, v207
	v_exp_f32_e32 v208, v208
	v_exp_f32_e32 v209, v209
	v_exp_f32_e32 v210, v210
	v_mul_f32_e32 v108, v108, v100
	v_mul_f32_e32 v109, v109, v101
	v_mul_f32_e32 v110, v110, v102
	v_mul_f32_e32 v111, v111, v103
	v_add_f32_e32 v207, 1.0, v207
	v_add_f32_e32 v208, 1.0, v208
	v_add_f32_e32 v209, 1.0, v209
	v_add_f32_e32 v210, 1.0, v210
	v_rcp_f32_e32 v207, v207
	v_rcp_f32_e32 v208, v208
	v_rcp_f32_e32 v209, v209
	v_rcp_f32_e32 v210, v210
	s_nop 0
	v_mul_f32_e32 v108, v108, v207
	v_mul_f32_e32 v109, v109, v208
	v_mul_f32_e32 v110, v110, v209
	v_mul_f32_e32 v111, v111, v210
	v_cvt_pk_bf16_f32 v100, v108, v109
	v_cvt_pk_bf16_f32 v101, v110, v111
	v_mul_f32_e32 v207, s71, v96
	v_mul_f32_e32 v208, s71, v97
	v_mul_f32_e32 v209, s71, v98
	v_mul_f32_e32 v210, s71, v99
	v_exp_f32_e32 v207, v207
	v_exp_f32_e32 v208, v208
	v_exp_f32_e32 v209, v209
	v_exp_f32_e32 v210, v210
	v_mul_f32_e32 v104, v104, v96
	v_mul_f32_e32 v105, v105, v97
	v_mul_f32_e32 v106, v106, v98
	v_mul_f32_e32 v107, v107, v99
	v_add_f32_e32 v207, 1.0, v207
	v_add_f32_e32 v208, 1.0, v208
	v_add_f32_e32 v209, 1.0, v209
	v_add_f32_e32 v210, 1.0, v210
	v_rcp_f32_e32 v207, v207
	v_rcp_f32_e32 v208, v208
	v_rcp_f32_e32 v209, v209
	v_rcp_f32_e32 v210, v210
	s_nop 0
	v_mul_f32_e32 v104, v104, v207
	v_mul_f32_e32 v105, v105, v208
	v_mul_f32_e32 v106, v106, v209
	v_mul_f32_e32 v107, v107, v210
	v_cvt_pk_bf16_f32 v96, v104, v105
	v_cvt_pk_bf16_f32 v97, v106, v107
	s_mov_b32 s1, 0x800
	s_and_b64 vcc, exec, s[36:37]
	s_cbranch_vccz .Lffn_hs
	s_mov_b32 s1, 0x1000
; #define PG8_LAS __attribute__((address_space(3)))
; __device__ __forceinline__ unsigned cvt_pk_bf16(float lo, float hi) { unsigned r; asm volatile("v_cvt_pk_bf16_f32 %0, %1, %2" : "=v"(r) : "v"(lo), "v"(hi)); return r; }
;     __device__ __forceinline__ void operator()(const f32x4 (&acc)[2][2][4][2], const Unit& u, int wr, int wc, int fr, int fq) const {
;     ...
;                 if (wr == 1 || ai == 1) { const int src = (wr == 1) ? (ai * 2 + 0) : (0 * 2 + 1);
; #pragma unroll
;                     for (int bj = 0; bj < 2; ++bj) { h14[bj] = *(const PG8_LAS f32x4*)(xch + (src * 4 + wc) * 128 + 0 * 64 + (bj * 2 + n) * 16 + fq * 4); h15[bj] = *(const PG8_LAS f32x4*)(xch + (src * 4 + wc) * 128 + 1 * 64 + (bj * 2 + n) * 16 + fq * 4); }
;                 } else {
; #pragma unroll
;                     for (int bj = 0; bj < 2; ++bj) { h14[bj] = (f32x4){0.f, 0.f, 0.f, 0.f}; h15[bj] = (f32x4){0.f, 0.f, 0.f, 0.f}; } }
; #pragma unroll
;                 for (int m = 0; m < 4; ++m) {
;                     float val[2][4];
; #pragma unroll
;                     for (int bj = 0; bj < 2; ++bj)
; #pragma unroll
;                         for (int jj = 0; jj < 4; ++jj) {
;                             const float cur = acc[ai][bj][m][n][jj];
;                             float o1, o2;
;                             if (m > 0) { const float pv = acc[ai][bj][m > 0 ? m - 1 : 0][n][jj]; o1 = dppf<0x121>(0.f, pv); o2 = dppf<0x122>(0.f, pv); }
;                             else { o1 = h15[bj][jj]; o2 = (fr == 0) ? h14[bj][jj] : h15[bj][jj]; }
;                             const float p1 = dppf<0x111>(o1, cur), p2 = dppf<0x112>(o2, cur);
;                             val[bj][jj] = w2[bj][jj] * cur + w1[bj][jj] * p1 + w0[bj][jj] * p2 + bb[bj][jj];
;                         }
;                     float y[4];
; #pragma unroll
;                     for (int jj = 0; jj < 4; ++jj) { const float g = val[1][jj]; y[jj] = val[0][jj] * g * __builtin_amdgcn_rcpf(1.0f + __builtin_amdgcn_exp2f(-1.4426950408889634f * g)); }
;                     u32x2 w; w.x = cvt_pk_bf16(y[0], y[1]); w.y = cvt_pk_bf16(y[2], y[3]);
.Lffn_hs:
	v_add_u32_e32 v206, s1, v214
	ds_read_b128 v[166:169], v206
	ds_read_b128 v[174:177], v206 offset:256
	ds_read_b128 v[170:173], v206 offset:128
	ds_read_b128 v[118:121], v206 offset:384
	s_waitcnt lgkmcnt(0)
	v_mov_b32_dpp v174, v72 row_shr:1 row_mask:0xf bank_mask:0xf
	v_mov_b32_dpp v175, v73 row_shr:1 row_mask:0xf bank_mask:0xf
	v_mov_b32_dpp v176, v74 row_shr:1 row_mask:0xf bank_mask:0xf
	v_mov_b32_dpp v177, v75 row_shr:1 row_mask:0xf bank_mask:0xf
	v_mov_b32_dpp v166, v76 row_shr:1 row_mask:0xf bank_mask:0xf
	v_mov_b32_dpp v167, v77 row_shr:1 row_mask:0xf bank_mask:0xf
	v_mov_b32_dpp v168, v78 row_shr:1 row_mask:0xf bank_mask:0xf
	v_mov_b32_dpp v169, v79 row_shr:1 row_mask:0xf bank_mask:0xf
	v_fma_f32 v72, v142, v72, v150
	v_fma_f32 v73, v143, v73, v151
	v_fma_f32 v74, v144, v74, v152
	v_fma_f32 v75, v145, v75, v153
	v_fmac_f32_e32 v72, v134, v76
	v_fmac_f32_e32 v73, v135, v77
	v_fmac_f32_e32 v74, v136, v78
	v_fmac_f32_e32 v75, v137, v79
	v_fmac_f32_e32 v72, v126, v84
	v_fmac_f32_e32 v73, v127, v85
	v_fmac_f32_e32 v74, v128, v86
	v_fmac_f32_e32 v75, v129, v87
	v_fma_f32 v76, v142, v76, v150
	v_fma_f32 v77, v143, v77, v151
	v_fma_f32 v78, v144, v78, v152
	v_fma_f32 v79, v145, v79, v153
	v_fmac_f32_e32 v76, v134, v84
	v_fmac_f32_e32 v77, v135, v85
	v_fmac_f32_e32 v78, v136, v86
	v_fmac_f32_e32 v79, v137, v87
	v_fmac_f32_e32 v76, v126, v92
	v_fmac_f32_e32 v77, v127, v93
	v_fmac_f32_e32 v78, v128, v94
	v_fmac_f32_e32 v79, v129, v95
	v_fma_f32 v84, v142, v84, v150
	v_fma_f32 v85, v143, v85, v151
	v_fma_f32 v86, v144, v86, v152
	v_fma_f32 v87, v145, v87, v153
	v_fmac_f32_e32 v84, v134, v92
	v_fmac_f32_e32 v85, v135, v93
	v_fmac_f32_e32 v86, v136, v94
	v_fmac_f32_e32 v87, v137, v95
	v_fmac_f32_e32 v84, v126, v174
	v_fmac_f32_e32 v85, v127, v175
	v_fmac_f32_e32 v86, v128, v176
	v_fmac_f32_e32 v87, v129, v177
	v_fma_f32 v92, v142, v92, v150
	v_fma_f32 v93, v143, v93, v151
	v_fma_f32 v94, v144, v94, v152
	v_fma_f32 v95, v145, v95, v153
	v_fmac_f32_e32 v92, v134, v174
	v_fmac_f32_e32 v93, v135, v175
	v_fmac_f32_e32 v94, v136, v176
	v_fmac_f32_e32 v95, v137, v177
	v_fmac_f32_e32 v92, v126, v166
	v_fmac_f32_e32 v93, v127, v167
	v_fmac_f32_e32 v94, v128, v168
	v_fmac_f32_e32 v95, v129, v169
	v_mov_b32_dpp v118, v64 row_shr:1 row_mask:0xf bank_mask:0xf
	v_mov_b32_dpp v119, v65 row_shr:1 row_mask:0xf bank_mask:0xf
	v_mov_b32_dpp v120, v66 row_shr:1 row_mask:0xf bank_mask:0xf
	v_mov_b32_dpp v121, v67 row_shr:1 row_mask:0xf bank_mask:0xf
	v_mov_b32_dpp v170, v68 row_shr:1 row_mask:0xf bank_mask:0xf
	v_mov_b32_dpp v171, v69 row_shr:1 row_mask:0xf bank_mask:0xf
	v_mov_b32_dpp v172, v70 row_shr:1 row_mask:0xf bank_mask:0xf
	v_mov_b32_dpp v173, v71 row_shr:1 row_mask:0xf bank_mask:0xf
	v_fma_f32 v64, v146, v64, v154
	v_fma_f32 v65, v147, v65, v155
	v_fma_f32 v66, v148, v66, v156
	v_fma_f32 v67, v149, v67, v157
	v_fmac_f32_e32 v64, v138, v68
	v_fmac_f32_e32 v65, v139, v69
	v_fmac_f32_e32 v66, v140, v70
	v_fmac_f32_e32 v67, v141, v71
	v_fmac_f32_e32 v64, v130, v80
	v_fmac_f32_e32 v65, v131, v81
	v_fmac_f32_e32 v66, v132, v82
	v_fmac_f32_e32 v67, v133, v83
	v_fma_f32 v68, v146, v68, v154
	v_fma_f32 v69, v147, v69, v155
	v_fma_f32 v70, v148, v70, v156
	v_fma_f32 v71, v149, v71, v157
	v_fmac_f32_e32 v68, v138, v80
	v_fmac_f32_e32 v69, v139, v81
	v_fmac_f32_e32 v70, v140, v82
	v_fmac_f32_e32 v71, v141, v83
	v_fmac_f32_e32 v68, v130, v88
	v_fmac_f32_e32 v69, v131, v89
	v_fmac_f32_e32 v70, v132, v90
	v_fmac_f32_e32 v71, v133, v91
	v_fma_f32 v80, v146, v80, v154
	v_fma_f32 v81, v147, v81, v155
	v_fma_f32 v82, v148, v82, v156
	v_fma_f32 v83, v149, v83, v157
	v_fmac_f32_e32 v80, v138, v88
	v_fmac_f32_e32 v81, v139, v89
	v_fmac_f32_e32 v82, v140, v90
	v_fmac_f32_e32 v83, v141, v91
	v_fmac_f32_e32 v80, v130, v118
	v_fmac_f32_e32 v81, v131, v119
	v_fmac_f32_e32 v82, v132, v120
	v_fmac_f32_e32 v83, v133, v121
	v_fma_f32 v88, v146, v88, v154
	v_fma_f32 v89, v147, v89, v155
	v_fma_f32 v90, v148, v90, v156
	v_fma_f32 v91, v149, v91, v157
	v_fmac_f32_e32 v88, v138, v118
	v_fmac_f32_e32 v89, v139, v119
	v_fmac_f32_e32 v90, v140, v120
	v_fmac_f32_e32 v91, v141, v121
	v_fmac_f32_e32 v88, v130, v170
	v_fmac_f32_e32 v89, v131, v171
	v_fmac_f32_e32 v90, v132, v172
	v_fmac_f32_e32 v91, v133, v173
	v_mul_f32_e32 v207, s71, v88
	v_mul_f32_e32 v208, s71, v89
	v_mul_f32_e32 v209, s71, v90
	v_mul_f32_e32 v210, s71, v91
	v_exp_f32_e32 v207, v207
	v_exp_f32_e32 v208, v208
	v_exp_f32_e32 v209, v209
	v_exp_f32_e32 v210, v210
	v_mul_f32_e32 v92, v92, v88
	v_mul_f32_e32 v93, v93, v89
	v_mul_f32_e32 v94, v94, v90
	v_mul_f32_e32 v95, v95, v91
	v_add_f32_e32 v207, 1.0, v207
	v_add_f32_e32 v208, 1.0, v208
	v_add_f32_e32 v209, 1.0, v209
	v_add_f32_e32 v210, 1.0, v210
	v_rcp_f32_e32 v207, v207
	v_rcp_f32_e32 v208, v208
	v_rcp_f32_e32 v209, v209
	v_rcp_f32_e32 v210, v210
	s_nop 0
	v_mul_f32_e32 v92, v92, v207
	v_mul_f32_e32 v93, v93, v208
	v_mul_f32_e32 v94, v94, v209
	v_mul_f32_e32 v95, v95, v210
	v_cvt_pk_bf16_f32 v88, v92, v93
	v_cvt_pk_bf16_f32 v89, v94, v95
	v_mul_f32_e32 v207, s71, v80
	v_mul_f32_e32 v208, s71, v81
	v_mul_f32_e32 v209, s71, v82
	v_mul_f32_e32 v210, s71, v83
	v_exp_f32_e32 v207, v207
	v_exp_f32_e32 v208, v208
	v_exp_f32_e32 v209, v209
	v_exp_f32_e32 v210, v210
	v_mul_f32_e32 v84, v84, v80
	v_mul_f32_e32 v85, v85, v81
	v_mul_f32_e32 v86, v86, v82
	v_mul_f32_e32 v87, v87, v83
	v_add_f32_e32 v207, 1.0, v207
	v_add_f32_e32 v208, 1.0, v208
	v_add_f32_e32 v209, 1.0, v209
	v_add_f32_e32 v210, 1.0, v210
	v_rcp_f32_e32 v207, v207
	v_rcp_f32_e32 v208, v208
	v_rcp_f32_e32 v209, v209
	v_rcp_f32_e32 v210, v210
	s_nop 0
	v_mul_f32_e32 v84, v84, v207
	v_mul_f32_e32 v85, v85, v208
; #define PG8_LAS __attribute__((address_space(3)))
;     __device__ __forceinline__ void operator()(const f32x4 (&acc)[2][2][4][2], const Unit& u, int wr, int wc, int fr, int fq) const {
;     ...
;             for (int bj = 0; bj < 2; ++bj) { w0[bj] = *(const f32x4*)(cw + bj * dff + ch0); w1[bj] = *(const f32x4*)(cw + upw + bj * dff + ch0); w2[bj] = *(const f32x4*)(cw + 2 * upw + bj * dff + ch0); bb[bj] = *(const f32x4*)(cb + bj * dff + ch0); }
; #pragma unroll
;             for (int ai = 0; ai < 2; ++ai) {
;                 f32x4 h15[2], h14[2];
;                 if (wr == 1 || ai == 1) { const int src = (wr == 1) ? (ai * 2 + 0) : (0 * 2 + 1);
; #pragma unroll
;                     for (int bj = 0; bj < 2; ++bj) { h14[bj] = *(const PG8_LAS f32x4*)(xch + (src * 4 + wc) * 128 + 0 * 64 + (bj * 2 + n) * 16 + fq * 4); h15[bj] = *(const PG8_LAS f32x4*)(xch + (src * 4 + wc) * 128 + 1 * 64 + (bj * 2 + n) * 16 + fq * 4); }
;                 } else {
; #pragma unroll
;                     for (int bj = 0; bj < 2; ++bj) { h14[bj] = (f32x4){0.f, 0.f, 0.f, 0.f}; h15[bj] = (f32x4){0.f, 0.f, 0.f, 0.f}; } }
; #pragma unroll
;                 for (int m = 0; m < 4; ++m) {
;                     float val[2][4];
; #pragma unroll
;                     for (int bj = 0; bj < 2; ++bj)
; #pragma unroll
;                         for (int jj = 0; jj < 4; ++jj) {
;                             const float cur = acc[ai][bj][m][n][jj];
;                             float o1, o2;
;                             if (m > 0) { const float pv = acc[ai][bj][m > 0 ? m - 1 : 0][n][jj]; o1 = dppf<0x121>(0.f, pv); o2 = dppf<0x122>(0.f, pv); }
;                             else { o1 = h15[bj][jj]; o2 = (fr == 0) ? h14[bj][jj] : h15[bj][jj]; }
;                             const float p1 = dppf<0x111>(o1, cur), p2 = dppf<0x112>(o2, cur);
;                             val[bj][jj] = w2[bj][jj] * cur + w1[bj][jj] * p1 + w0[bj][jj] * p2 + bb[bj][jj];
;                         }
;                     float y[4];
; #pragma unroll
;                     for (int jj = 0; jj < 4; ++jj) { const float g = val[1][jj]; y[jj] = val[0][jj] * g * __builtin_amdgcn_rcpf(1.0f + __builtin_amdgcn_exp2f(-1.4426950408889634f * g)); }
;                     u32x2 w; w.x = cvt_pk_bf16(y[0], y[1]); w.y = cvt_pk_bf16(y[2], y[3]);
	v_mul_f32_e32 v86, v86, v209
	v_mul_f32_e32 v87, v87, v210
	v_cvt_pk_bf16_f32 v80, v84, v85
	v_cvt_pk_bf16_f32 v81, v86, v87
	v_mul_f32_e32 v207, s71, v68
	v_mul_f32_e32 v208, s71, v69
	v_mul_f32_e32 v209, s71, v70
	v_mul_f32_e32 v210, s71, v71
	v_exp_f32_e32 v207, v207
	v_exp_f32_e32 v208, v208
	v_exp_f32_e32 v209, v209
	v_exp_f32_e32 v210, v210
	v_mul_f32_e32 v76, v76, v68
	v_mul_f32_e32 v77, v77, v69
	v_mul_f32_e32 v78, v78, v70
	v_mul_f32_e32 v79, v79, v71
	v_add_f32_e32 v207, 1.0, v207
	v_add_f32_e32 v208, 1.0, v208
	v_add_f32_e32 v209, 1.0, v209
	v_add_f32_e32 v210, 1.0, v210
	v_rcp_f32_e32 v207, v207
	v_rcp_f32_e32 v208, v208
	v_rcp_f32_e32 v209, v209
	v_rcp_f32_e32 v210, v210
	s_nop 0
	v_mul_f32_e32 v76, v76, v207
	v_mul_f32_e32 v77, v77, v208
	v_mul_f32_e32 v78, v78, v209
	v_mul_f32_e32 v79, v79, v210
	v_cvt_pk_bf16_f32 v68, v76, v77
	v_cvt_pk_bf16_f32 v69, v78, v79
	v_mul_f32_e32 v207, s71, v64
	v_mul_f32_e32 v208, s71, v65
	v_mul_f32_e32 v209, s71, v66
	v_mul_f32_e32 v210, s71, v67
	v_exp_f32_e32 v207, v207
	v_exp_f32_e32 v208, v208
	v_exp_f32_e32 v209, v209
	v_exp_f32_e32 v210, v210
	v_mul_f32_e32 v72, v72, v64
	v_mul_f32_e32 v73, v73, v65
	v_mul_f32_e32 v74, v74, v66
	v_mul_f32_e32 v75, v75, v67
	v_add_f32_e32 v207, 1.0, v207
	v_add_f32_e32 v208, 1.0, v208
	v_add_f32_e32 v209, 1.0, v209
	v_add_f32_e32 v210, 1.0, v210
	v_rcp_f32_e32 v207, v207
	v_rcp_f32_e32 v208, v208
	v_rcp_f32_e32 v209, v209
	v_rcp_f32_e32 v210, v210
	s_nop 0
	v_mul_f32_e32 v72, v72, v207
	v_mul_f32_e32 v73, v73, v208
	v_mul_f32_e32 v74, v74, v209
	v_mul_f32_e32 v75, v75, v210
	v_cvt_pk_bf16_f32 v64, v72, v73
	v_cvt_pk_bf16_f32 v65, v74, v75
	global_load_dwordx4 v[126:129], v112, s[26:27] offset:16
	global_load_dwordx4 v[130:133], v113, s[26:27] offset:16
	global_load_dwordx4 v[134:137], v112, s[58:59] offset:16
	global_load_dwordx4 v[138:141], v113, s[58:59] offset:16
	global_load_dwordx4 v[142:145], v112, s[60:61] offset:16
	global_load_dwordx4 v[146:149], v113, s[60:61] offset:16
	global_load_dwordx4 v[150:153], v112, s[44:45] offset:16
	global_load_dwordx4 v[154:157], v113, s[44:45] offset:16
	v_mov_b32_e32 v166, 0
	v_mov_b32_e32 v174, 0
	v_mov_b32_e32 v167, 0
	v_mov_b32_e32 v175, 0
	v_mov_b32_e32 v168, 0
	v_mov_b32_e32 v176, 0
	v_mov_b32_e32 v169, 0
	v_mov_b32_e32 v177, 0
	v_mov_b32_e32 v170, 0
	v_mov_b32_e32 v118, 0
	v_mov_b32_e32 v171, 0
	v_mov_b32_e32 v119, 0
	v_mov_b32_e32 v172, 0
	v_mov_b32_e32 v120, 0
	v_mov_b32_e32 v173, 0
	v_mov_b32_e32 v121, 0
	s_and_b64 vcc, exec, s[36:37]
	s_cbranch_vccz .Lffn_h10
	ds_read_b128 v[166:169], v214 offset:64
	ds_read_b128 v[174:177], v214 offset:320
	ds_read_b128 v[170:173], v214 offset:192
	ds_read_b128 v[118:121], v214 offset:448
.Lffn_h10:
	s_waitcnt vmcnt(0) lgkmcnt(0)
	v_mov_b32_dpp v174, v40 row_shr:1 row_mask:0xf bank_mask:0xf
	v_mov_b32_dpp v175, v41 row_shr:1 row_mask:0xf bank_mask:0xf
	v_mov_b32_dpp v176, v42 row_shr:1 row_mask:0xf bank_mask:0xf
	v_mov_b32_dpp v177, v43 row_shr:1 row_mask:0xf bank_mask:0xf
	v_mov_b32_dpp v166, v44 row_shr:1 row_mask:0xf bank_mask:0xf
	v_mov_b32_dpp v167, v45 row_shr:1 row_mask:0xf bank_mask:0xf
	v_mov_b32_dpp v168, v46 row_shr:1 row_mask:0xf bank_mask:0xf
	v_mov_b32_dpp v169, v47 row_shr:1 row_mask:0xf bank_mask:0xf
	v_fma_f32 v40, v142, v40, v150
	v_fma_f32 v41, v143, v41, v151
	v_fma_f32 v42, v144, v42, v152
	v_fma_f32 v43, v145, v43, v153
	v_fmac_f32_e32 v40, v134, v44
	v_fmac_f32_e32 v41, v135, v45
	v_fmac_f32_e32 v42, v136, v46
	v_fmac_f32_e32 v43, v137, v47
	v_fmac_f32_e32 v40, v126, v52
	v_fmac_f32_e32 v41, v127, v53
	v_fmac_f32_e32 v42, v128, v54
	v_fmac_f32_e32 v43, v129, v55
	v_fma_f32 v44, v142, v44, v150
	v_fma_f32 v45, v143, v45, v151
	v_fma_f32 v46, v144, v46, v152
	v_fma_f32 v47, v145, v47, v153
	v_fmac_f32_e32 v44, v134, v52
	v_fmac_f32_e32 v45, v135, v53
	v_fmac_f32_e32 v46, v136, v54
	v_fmac_f32_e32 v47, v137, v55
	v_fmac_f32_e32 v44, v126, v60
	v_fmac_f32_e32 v45, v127, v61
	v_fmac_f32_e32 v46, v128, v62
	v_fmac_f32_e32 v47, v129, v63
	v_fma_f32 v52, v142, v52, v150
	v_fma_f32 v53, v143, v53, v151
	v_fma_f32 v54, v144, v54, v152
	v_fma_f32 v55, v145, v55, v153
	v_fmac_f32_e32 v52, v134, v60
	v_fmac_f32_e32 v53, v135, v61
	v_fmac_f32_e32 v54, v136, v62
	v_fmac_f32_e32 v55, v137, v63
	v_fmac_f32_e32 v52, v126, v174
	v_fmac_f32_e32 v53, v127, v175
	v_fmac_f32_e32 v54, v128, v176
	v_fmac_f32_e32 v55, v129, v177
	v_fma_f32 v60, v142, v60, v150
	v_fma_f32 v61, v143, v61, v151
	v_fma_f32 v62, v144, v62, v152
	v_fma_f32 v63, v145, v63, v153
	v_fmac_f32_e32 v60, v134, v174
	v_fmac_f32_e32 v61, v135, v175
	v_fmac_f32_e32 v62, v136, v176
	v_fmac_f32_e32 v63, v137, v177
	v_fmac_f32_e32 v60, v126, v166
	v_fmac_f32_e32 v61, v127, v167
	v_fmac_f32_e32 v62, v128, v168
	v_fmac_f32_e32 v63, v129, v169
	v_mov_b32_dpp v118, v32 row_shr:1 row_mask:0xf bank_mask:0xf
	v_mov_b32_dpp v119, v33 row_shr:1 row_mask:0xf bank_mask:0xf
	v_mov_b32_dpp v120, v34 row_shr:1 row_mask:0xf bank_mask:0xf
	v_mov_b32_dpp v121, v35 row_shr:1 row_mask:0xf bank_mask:0xf
	v_mov_b32_dpp v170, v36 row_shr:1 row_mask:0xf bank_mask:0xf
	v_mov_b32_dpp v171, v37 row_shr:1 row_mask:0xf bank_mask:0xf
	v_mov_b32_dpp v172, v38 row_shr:1 row_mask:0xf bank_mask:0xf
	v_mov_b32_dpp v173, v39 row_shr:1 row_mask:0xf bank_mask:0xf
	v_fma_f32 v32, v146, v32, v154
	v_fma_f32 v33, v147, v33, v155
	v_fma_f32 v34, v148, v34, v156
	v_fma_f32 v35, v149, v35, v157
	v_fmac_f32_e32 v32, v138, v36
	v_fmac_f32_e32 v33, v139, v37
	v_fmac_f32_e32 v34, v140, v38
	v_fmac_f32_e32 v35, v141, v39
	v_fmac_f32_e32 v32, v130, v48
	v_fmac_f32_e32 v33, v131, v49
	v_fmac_f32_e32 v34, v132, v50
	v_fmac_f32_e32 v35, v133, v51
; __device__ __forceinline__ unsigned cvt_pk_bf16(float lo, float hi) { unsigned r; asm volatile("v_cvt_pk_bf16_f32 %0, %1, %2" : "=v"(r) : "v"(lo), "v"(hi)); return r; }
;     __device__ __forceinline__ void operator()(const f32x4 (&acc)[2][2][4][2], const Unit& u, int wr, int wc, int fr, int fq) const {
;     ...
;                 for (int m = 0; m < 4; ++m) {
;                     float val[2][4];
; #pragma unroll
;                     for (int bj = 0; bj < 2; ++bj)
; #pragma unroll
;                         for (int jj = 0; jj < 4; ++jj) {
;                             const float cur = acc[ai][bj][m][n][jj];
;                             float o1, o2;
;                             if (m > 0) { const float pv = acc[ai][bj][m > 0 ? m - 1 : 0][n][jj]; o1 = dppf<0x121>(0.f, pv); o2 = dppf<0x122>(0.f, pv); }
;                             else { o1 = h15[bj][jj]; o2 = (fr == 0) ? h14[bj][jj] : h15[bj][jj]; }
;                             const float p1 = dppf<0x111>(o1, cur), p2 = dppf<0x112>(o2, cur);
;                             val[bj][jj] = w2[bj][jj] * cur + w1[bj][jj] * p1 + w0[bj][jj] * p2 + bb[bj][jj];
;                         }
;                     float y[4];
; #pragma unroll
;                     for (int jj = 0; jj < 4; ++jj) { const float g = val[1][jj]; y[jj] = val[0][jj] * g * __builtin_amdgcn_rcpf(1.0f + __builtin_amdgcn_exp2f(-1.4426950408889634f * g)); }
;                     u32x2 w; w.x = cvt_pk_bf16(y[0], y[1]); w.y = cvt_pk_bf16(y[2], y[3]);
;                     if (n == 0) keep[ai][m] = w;
;                     else { const int row = u.pm * BM + ai * HALF + wr * 64 + m * 16 + fr;
;                         u32x4 w4; w4.x = keep[ai][m].x; w4.y = keep[ai][m].y; w4.z = w.x; w4.w = w.y;
;                         *(u32x4*)(act + (size_t)row * dff + ch0 - 4) = w4; }
	v_fma_f32 v36, v146, v36, v154
	v_fma_f32 v37, v147, v37, v155
	v_fma_f32 v38, v148, v38, v156
	v_fma_f32 v39, v149, v39, v157
	v_fmac_f32_e32 v36, v138, v48
	v_fmac_f32_e32 v37, v139, v49
	v_fmac_f32_e32 v38, v140, v50
	v_fmac_f32_e32 v39, v141, v51
	v_fmac_f32_e32 v36, v130, v56
	v_fmac_f32_e32 v37, v131, v57
	v_fmac_f32_e32 v38, v132, v58
	v_fmac_f32_e32 v39, v133, v59
	v_fma_f32 v48, v146, v48, v154
	v_fma_f32 v49, v147, v49, v155
	v_fma_f32 v50, v148, v50, v156
	v_fma_f32 v51, v149, v51, v157
	v_fmac_f32_e32 v48, v138, v56
	v_fmac_f32_e32 v49, v139, v57
	v_fmac_f32_e32 v50, v140, v58
	v_fmac_f32_e32 v51, v141, v59
	v_fmac_f32_e32 v48, v130, v118
	v_fmac_f32_e32 v49, v131, v119
	v_fmac_f32_e32 v50, v132, v120
	v_fmac_f32_e32 v51, v133, v121
	v_fma_f32 v56, v146, v56, v154
	v_fma_f32 v57, v147, v57, v155
	v_fma_f32 v58, v148, v58, v156
	v_fma_f32 v59, v149, v59, v157
	v_fmac_f32_e32 v56, v138, v118
	v_fmac_f32_e32 v57, v139, v119
	v_fmac_f32_e32 v58, v140, v120
	v_fmac_f32_e32 v59, v141, v121
	v_fmac_f32_e32 v56, v130, v170
	v_fmac_f32_e32 v57, v131, v171
	v_fmac_f32_e32 v58, v132, v172
	v_fmac_f32_e32 v59, v133, v173
	v_mul_f32_e32 v207, s71, v56
	v_mul_f32_e32 v208, s71, v57
	v_mul_f32_e32 v209, s71, v58
	v_mul_f32_e32 v210, s71, v59
	v_exp_f32_e32 v207, v207
	v_exp_f32_e32 v208, v208
	v_exp_f32_e32 v209, v209
	v_exp_f32_e32 v210, v210
	v_mul_f32_e32 v60, v60, v56
	v_mul_f32_e32 v61, v61, v57
	v_mul_f32_e32 v62, v62, v58
	v_mul_f32_e32 v63, v63, v59
	v_add_f32_e32 v207, 1.0, v207
	v_add_f32_e32 v208, 1.0, v208
	v_add_f32_e32 v209, 1.0, v209
	v_add_f32_e32 v210, 1.0, v210
	v_rcp_f32_e32 v207, v207
	v_rcp_f32_e32 v208, v208
	v_rcp_f32_e32 v209, v209
	v_rcp_f32_e32 v210, v210
	s_nop 0
	v_mul_f32_e32 v60, v60, v207
	v_mul_f32_e32 v61, v61, v208
	v_mul_f32_e32 v62, v62, v209
	v_mul_f32_e32 v63, v63, v210
	v_cvt_pk_bf16_f32 v160, v60, v61
	v_cvt_pk_bf16_f32 v161, v62, v63
	global_store_dwordx4 v188, v[158:161], s[30:31]
	s_add_u32 s30, s30, 0x2c00
	s_addc_u32 s31, s31, 0
	v_mul_f32_e32 v207, s71, v48
	v_mul_f32_e32 v208, s71, v49
	v_mul_f32_e32 v209, s71, v50
	v_mul_f32_e32 v210, s71, v51
	v_exp_f32_e32 v207, v207
	v_exp_f32_e32 v208, v208
	v_exp_f32_e32 v209, v209
	v_exp_f32_e32 v210, v210
	v_mul_f32_e32 v52, v52, v48
	v_mul_f32_e32 v53, v53, v49
	v_mul_f32_e32 v54, v54, v50
	v_mul_f32_e32 v55, v55, v51
	v_add_f32_e32 v207, 1.0, v207
	v_add_f32_e32 v208, 1.0, v208
	v_add_f32_e32 v209, 1.0, v209
	v_add_f32_e32 v210, 1.0, v210
	v_rcp_f32_e32 v207, v207
	v_rcp_f32_e32 v208, v208
	v_rcp_f32_e32 v209, v209
	v_rcp_f32_e32 v210, v210
	s_nop 0
	v_mul_f32_e32 v52, v52, v207
	v_mul_f32_e32 v53, v53, v208
	v_mul_f32_e32 v54, v54, v209
	v_mul_f32_e32 v55, v55, v210
	v_cvt_pk_bf16_f32 v116, v52, v53
	v_cvt_pk_bf16_f32 v117, v54, v55
	global_store_dwordx4 v188, v[114:117], s[30:31]
	s_add_u32 s30, s30, 0x2c00
	s_addc_u32 s31, s31, 0
	v_mul_f32_e32 v207, s71, v36
	v_mul_f32_e32 v208, s71, v37
	v_mul_f32_e32 v209, s71, v38
	v_mul_f32_e32 v210, s71, v39
	v_exp_f32_e32 v207, v207
	v_exp_f32_e32 v208, v208
	v_exp_f32_e32 v209, v209
	v_exp_f32_e32 v210, v210
	v_mul_f32_e32 v44, v44, v36
	v_mul_f32_e32 v45, v45, v37
	v_mul_f32_e32 v46, v46, v38
	v_mul_f32_e32 v47, v47, v39
	v_add_f32_e32 v207, 1.0, v207
	v_add_f32_e32 v208, 1.0, v208
	v_add_f32_e32 v209, 1.0, v209
	v_add_f32_e32 v210, 1.0, v210
	v_rcp_f32_e32 v207, v207
	v_rcp_f32_e32 v208, v208
	v_rcp_f32_e32 v209, v209
	v_rcp_f32_e32 v210, v210
	s_nop 0
	v_mul_f32_e32 v44, v44, v207
	v_mul_f32_e32 v45, v45, v208
	v_mul_f32_e32 v46, v46, v209
	v_mul_f32_e32 v47, v47, v210
	v_cvt_pk_bf16_f32 v102, v44, v45
	v_cvt_pk_bf16_f32 v103, v46, v47
	global_store_dwordx4 v188, v[100:103], s[30:31]
	s_add_u32 s30, s30, 0x2c00
	s_addc_u32 s31, s31, 0
	v_mul_f32_e32 v207, s71, v32
	v_mul_f32_e32 v208, s71, v33
	v_mul_f32_e32 v209, s71, v34
	v_mul_f32_e32 v210, s71, v35
	v_exp_f32_e32 v207, v207
	v_exp_f32_e32 v208, v208
	v_exp_f32_e32 v209, v209
	v_exp_f32_e32 v210, v210
	v_mul_f32_e32 v40, v40, v32
	v_mul_f32_e32 v41, v41, v33
	v_mul_f32_e32 v42, v42, v34
	v_mul_f32_e32 v43, v43, v35
	v_add_f32_e32 v207, 1.0, v207
	v_add_f32_e32 v208, 1.0, v208
	v_add_f32_e32 v209, 1.0, v209
	v_add_f32_e32 v210, 1.0, v210
	v_rcp_f32_e32 v207, v207
	v_rcp_f32_e32 v208, v208
	v_rcp_f32_e32 v209, v209
	v_rcp_f32_e32 v210, v210
	s_nop 0
	v_mul_f32_e32 v40, v40, v207
	v_mul_f32_e32 v41, v41, v208
	v_mul_f32_e32 v42, v42, v209
	v_mul_f32_e32 v43, v43, v210
	v_cvt_pk_bf16_f32 v98, v40, v41
	v_cvt_pk_bf16_f32 v99, v42, v43
	global_store_dwordx4 v188, v[96:99], s[30:31]
	s_add_u32 s30, s30, 0x157c00
	s_addc_u32 s31, s31, 0
	ds_read_b128 v[166:169], v206 offset:64
	ds_read_b128 v[174:177], v206 offset:320
	ds_read_b128 v[170:173], v206 offset:192
	ds_read_b128 v[118:121], v206 offset:448
	s_waitcnt lgkmcnt(0)
;     __device__ __forceinline__ void operator()(const f32x4 (&acc)[2][2][4][2], const Unit& u, int wr, int wc, int fr, int fq) const {
;     ...
;                         for (int jj = 0; jj < 4; ++jj) {
;                             const float cur = acc[ai][bj][m][n][jj];
;                             float o1, o2;
;                             if (m > 0) { const float pv = acc[ai][bj][m > 0 ? m - 1 : 0][n][jj]; o1 = dppf<0x121>(0.f, pv); o2 = dppf<0x122>(0.f, pv); }
;                             else { o1 = h15[bj][jj]; o2 = (fr == 0) ? h14[bj][jj] : h15[bj][jj]; }
;                             const float p1 = dppf<0x111>(o1, cur), p2 = dppf<0x112>(o2, cur);
;                             val[bj][jj] = w2[bj][jj] * cur + w1[bj][jj] * p1 + w0[bj][jj] * p2 + bb[bj][jj];
;                         }
	v_mov_b32_dpp v174, v8 row_shr:1 row_mask:0xf bank_mask:0xf
	v_mov_b32_dpp v175, v9 row_shr:1 row_mask:0xf bank_mask:0xf
	v_mov_b32_dpp v176, v10 row_shr:1 row_mask:0xf bank_mask:0xf
	v_mov_b32_dpp v177, v11 row_shr:1 row_mask:0xf bank_mask:0xf
	v_mov_b32_dpp v166, v12 row_shr:1 row_mask:0xf bank_mask:0xf
	v_mov_b32_dpp v167, v13 row_shr:1 row_mask:0xf bank_mask:0xf
	v_mov_b32_dpp v168, v14 row_shr:1 row_mask:0xf bank_mask:0xf
	v_mov_b32_dpp v169, v15 row_shr:1 row_mask:0xf bank_mask:0xf
	v_fma_f32 v8, v142, v8, v150
	v_fma_f32 v9, v143, v9, v151
	v_fma_f32 v10, v144, v10, v152
	v_fma_f32 v11, v145, v11, v153
	v_fmac_f32_e32 v8, v134, v12
	v_fmac_f32_e32 v9, v135, v13
	v_fmac_f32_e32 v10, v136, v14
	v_fmac_f32_e32 v11, v137, v15
	v_fmac_f32_e32 v8, v126, v20
	v_fmac_f32_e32 v9, v127, v21
	v_fmac_f32_e32 v10, v128, v22
	v_fmac_f32_e32 v11, v129, v23
	v_fma_f32 v12, v142, v12, v150
	v_fma_f32 v13, v143, v13, v151
	v_fma_f32 v14, v144, v14, v152
	v_fma_f32 v15, v145, v15, v153
	v_fmac_f32_e32 v12, v134, v20
	v_fmac_f32_e32 v13, v135, v21
	v_fmac_f32_e32 v14, v136, v22
	v_fmac_f32_e32 v15, v137, v23
	v_fmac_f32_e32 v12, v126, v28
	v_fmac_f32_e32 v13, v127, v29
	v_fmac_f32_e32 v14, v128, v30
	v_fmac_f32_e32 v15, v129, v31
	v_fma_f32 v20, v142, v20, v150
	v_fma_f32 v21, v143, v21, v151
	v_fma_f32 v22, v144, v22, v152
	v_fma_f32 v23, v145, v23, v153
	v_fmac_f32_e32 v20, v134, v28
	v_fmac_f32_e32 v21, v135, v29
	v_fmac_f32_e32 v22, v136, v30
	v_fmac_f32_e32 v23, v137, v31
	v_fmac_f32_e32 v20, v126, v174
	v_fmac_f32_e32 v21, v127, v175
	v_fmac_f32_e32 v22, v128, v176
	v_fmac_f32_e32 v23, v129, v177
	v_fma_f32 v28, v142, v28, v150
	v_fma_f32 v29, v143, v29, v151
	v_fma_f32 v30, v144, v30, v152
	v_fma_f32 v31, v145, v31, v153
	v_fmac_f32_e32 v28, v134, v174
	v_fmac_f32_e32 v29, v135, v175
	v_fmac_f32_e32 v30, v136, v176
	v_fmac_f32_e32 v31, v137, v177
	v_fmac_f32_e32 v28, v126, v166
	v_fmac_f32_e32 v29, v127, v167
	v_fmac_f32_e32 v30, v128, v168
	v_fmac_f32_e32 v31, v129, v169
	v_mov_b32_dpp v118, v0 row_shr:1 row_mask:0xf bank_mask:0xf
	v_mov_b32_dpp v119, v1 row_shr:1 row_mask:0xf bank_mask:0xf
	v_mov_b32_dpp v120, v2 row_shr:1 row_mask:0xf bank_mask:0xf
	v_mov_b32_dpp v121, v3 row_shr:1 row_mask:0xf bank_mask:0xf
	v_mov_b32_dpp v170, v4 row_shr:1 row_mask:0xf bank_mask:0xf
	v_mov_b32_dpp v171, v5 row_shr:1 row_mask:0xf bank_mask:0xf
	v_mov_b32_dpp v172, v6 row_shr:1 row_mask:0xf bank_mask:0xf
	v_mov_b32_dpp v173, v7 row_shr:1 row_mask:0xf bank_mask:0xf
	v_fma_f32 v0, v146, v0, v154
	v_fma_f32 v1, v147, v1, v155
	v_fma_f32 v2, v148, v2, v156
	v_fma_f32 v3, v149, v3, v157
	v_fmac_f32_e32 v0, v138, v4
	v_fmac_f32_e32 v1, v139, v5
	v_fmac_f32_e32 v2, v140, v6
	v_fmac_f32_e32 v3, v141, v7
	v_fmac_f32_e32 v0, v130, v16
	v_fmac_f32_e32 v1, v131, v17
	v_fmac_f32_e32 v2, v132, v18
	v_fmac_f32_e32 v3, v133, v19
	v_fma_f32 v4, v146, v4, v154
	v_fma_f32 v5, v147, v5, v155
	v_fma_f32 v6, v148, v6, v156
	v_fma_f32 v7, v149, v7, v157
	v_fmac_f32_e32 v4, v138, v16
	v_fmac_f32_e32 v5, v139, v17
	v_fmac_f32_e32 v6, v140, v18
	v_fmac_f32_e32 v7, v141, v19
	v_fmac_f32_e32 v4, v130, v24
	v_fmac_f32_e32 v5, v131, v25
	v_fmac_f32_e32 v6, v132, v26
	v_fmac_f32_e32 v7, v133, v27
	v_fma_f32 v16, v146, v16, v154
	v_fma_f32 v17, v147, v17, v155
	v_fma_f32 v18, v148, v18, v156
	v_fma_f32 v19, v149, v19, v157
	v_fmac_f32_e32 v16, v138, v24
	v_fmac_f32_e32 v17, v139, v25
	v_fmac_f32_e32 v18, v140, v26
	v_fmac_f32_e32 v19, v141, v27
	v_fmac_f32_e32 v16, v130, v118
	v_fmac_f32_e32 v17, v131, v119
	v_fmac_f32_e32 v18, v132, v120
	v_fmac_f32_e32 v19, v133, v121
	v_fma_f32 v24, v146, v24, v154
	v_fma_f32 v25, v147, v25, v155
	v_fma_f32 v26, v148, v26, v156
	v_fma_f32 v27, v149, v27, v157
	v_fmac_f32_e32 v24, v138, v118
	v_fmac_f32_e32 v25, v139, v119
; __device__ __forceinline__ unsigned cvt_pk_bf16(float lo, float hi) { unsigned r; asm volatile("v_cvt_pk_bf16_f32 %0, %1, %2" : "=v"(r) : "v"(lo), "v"(hi)); return r; }
; #define PG8_BAR __builtin_amdgcn_s_barrier()
;     __device__ __forceinline__ void operator()(const f32x4 (&acc)[2][2][4][2], const Unit& u, int wr, int wc, int fr, int fq) const {
;     ...
;                     float y[4];
; #pragma unroll
;                     for (int jj = 0; jj < 4; ++jj) { const float g = val[1][jj]; y[jj] = val[0][jj] * g * __builtin_amdgcn_rcpf(1.0f + __builtin_amdgcn_exp2f(-1.4426950408889634f * g)); }
;                     u32x2 w; w.x = cvt_pk_bf16(y[0], y[1]); w.y = cvt_pk_bf16(y[2], y[3]);
;                     if (n == 0) keep[ai][m] = w;
;                     else { const int row = u.pm * BM + ai * HALF + wr * 64 + m * 16 + fr;
;                         u32x4 w4; w4.x = keep[ai][m].x; w4.y = keep[ai][m].y; w4.z = w.x; w4.w = w.y;
;                         *(u32x4*)(act + (size_t)row * dff + ch0 - 4) = w4; }
; template <class Epi, class Sched, bool ALIGN_EPI = false, bool SP2 = false>
; __device__ __forceinline__ void gemm_phase(PG8_LAS unsigned char* lds, const Gemm g, const Sched& S, const Epi& E) {
;     ...
;         cur = nxt; cA = nA; cB = nB; ++ui;
;         if constexpr (ALIGN_EPI) { if (wr == 1) PG8_BAR; }
	v_fmac_f32_e32 v26, v140, v120
	v_fmac_f32_e32 v27, v141, v121
	v_fmac_f32_e32 v24, v130, v170
	v_fmac_f32_e32 v25, v131, v171
	v_fmac_f32_e32 v26, v132, v172
	v_fmac_f32_e32 v27, v133, v173
	v_mul_f32_e32 v207, s71, v24
	v_mul_f32_e32 v208, s71, v25
	v_mul_f32_e32 v209, s71, v26
	v_mul_f32_e32 v210, s71, v27
	v_exp_f32_e32 v207, v207
	v_exp_f32_e32 v208, v208
	v_exp_f32_e32 v209, v209
	v_exp_f32_e32 v210, v210
	v_mul_f32_e32 v28, v28, v24
	v_mul_f32_e32 v29, v29, v25
	v_mul_f32_e32 v30, v30, v26
	v_mul_f32_e32 v31, v31, v27
	v_add_f32_e32 v207, 1.0, v207
	v_add_f32_e32 v208, 1.0, v208
	v_add_f32_e32 v209, 1.0, v209
	v_add_f32_e32 v210, 1.0, v210
	v_rcp_f32_e32 v207, v207
	v_rcp_f32_e32 v208, v208
	v_rcp_f32_e32 v209, v209
	v_rcp_f32_e32 v210, v210
	s_nop 0
	v_mul_f32_e32 v28, v28, v207
	v_mul_f32_e32 v29, v29, v208
	v_mul_f32_e32 v30, v30, v209
	v_mul_f32_e32 v31, v31, v210
	v_cvt_pk_bf16_f32 v90, v28, v29
	v_cvt_pk_bf16_f32 v91, v30, v31
	global_store_dwordx4 v188, v[88:91], s[30:31]
	s_add_u32 s30, s30, 0x2c00
	s_addc_u32 s31, s31, 0
	v_mul_f32_e32 v207, s71, v16
	v_mul_f32_e32 v208, s71, v17
	v_mul_f32_e32 v209, s71, v18
	v_mul_f32_e32 v210, s71, v19
	v_exp_f32_e32 v207, v207
	v_exp_f32_e32 v208, v208
	v_exp_f32_e32 v209, v209
	v_exp_f32_e32 v210, v210
	v_mul_f32_e32 v20, v20, v16
	v_mul_f32_e32 v21, v21, v17
	v_mul_f32_e32 v22, v22, v18
	v_mul_f32_e32 v23, v23, v19
	v_add_f32_e32 v207, 1.0, v207
	v_add_f32_e32 v208, 1.0, v208
	v_add_f32_e32 v209, 1.0, v209
	v_add_f32_e32 v210, 1.0, v210
	v_rcp_f32_e32 v207, v207
	v_rcp_f32_e32 v208, v208
	v_rcp_f32_e32 v209, v209
	v_rcp_f32_e32 v210, v210
	s_nop 0
	v_mul_f32_e32 v20, v20, v207
	v_mul_f32_e32 v21, v21, v208
	v_mul_f32_e32 v22, v22, v209
	v_mul_f32_e32 v23, v23, v210
	v_cvt_pk_bf16_f32 v82, v20, v21
	v_cvt_pk_bf16_f32 v83, v22, v23
	global_store_dwordx4 v188, v[80:83], s[30:31]
	s_add_u32 s30, s30, 0x2c00
	s_addc_u32 s31, s31, 0
	v_mul_f32_e32 v207, s71, v4
	v_mul_f32_e32 v208, s71, v5
	v_mul_f32_e32 v209, s71, v6
	v_mul_f32_e32 v210, s71, v7
	v_exp_f32_e32 v207, v207
	v_exp_f32_e32 v208, v208
	v_exp_f32_e32 v209, v209
	v_exp_f32_e32 v210, v210
	v_mul_f32_e32 v12, v12, v4
	v_mul_f32_e32 v13, v13, v5
	v_mul_f32_e32 v14, v14, v6
	v_mul_f32_e32 v15, v15, v7
	v_add_f32_e32 v207, 1.0, v207
	v_add_f32_e32 v208, 1.0, v208
	v_add_f32_e32 v209, 1.0, v209
	v_add_f32_e32 v210, 1.0, v210
	v_rcp_f32_e32 v207, v207
	v_rcp_f32_e32 v208, v208
	v_rcp_f32_e32 v209, v209
	v_rcp_f32_e32 v210, v210
	s_nop 0
	v_mul_f32_e32 v12, v12, v207
	v_mul_f32_e32 v13, v13, v208
	v_mul_f32_e32 v14, v14, v209
	v_mul_f32_e32 v15, v15, v210
	v_cvt_pk_bf16_f32 v70, v12, v13
	v_cvt_pk_bf16_f32 v71, v14, v15
	global_store_dwordx4 v188, v[68:71], s[30:31]
	s_add_u32 s30, s30, 0x2c00
	s_addc_u32 s31, s31, 0
	v_mul_f32_e32 v207, s71, v0
	v_mul_f32_e32 v208, s71, v1
	v_mul_f32_e32 v209, s71, v2
	v_mul_f32_e32 v210, s71, v3
	v_exp_f32_e32 v207, v207
	v_exp_f32_e32 v208, v208
	v_exp_f32_e32 v209, v209
	v_exp_f32_e32 v210, v210
	v_mul_f32_e32 v8, v8, v0
	v_mul_f32_e32 v9, v9, v1
	v_mul_f32_e32 v10, v10, v2
	v_mul_f32_e32 v11, v11, v3
	v_add_f32_e32 v207, 1.0, v207
	v_add_f32_e32 v208, 1.0, v208
	v_add_f32_e32 v209, 1.0, v209
	v_add_f32_e32 v210, 1.0, v210
	v_rcp_f32_e32 v207, v207
	v_rcp_f32_e32 v208, v208
	v_rcp_f32_e32 v209, v209
	v_rcp_f32_e32 v210, v210
	s_nop 0
	v_mul_f32_e32 v8, v8, v207
	v_mul_f32_e32 v9, v9, v208
	v_mul_f32_e32 v10, v10, v209
	v_mul_f32_e32 v11, v11, v210
	v_cvt_pk_bf16_f32 v66, v8, v9
	v_cvt_pk_bf16_f32 v67, v10, v11
	global_store_dwordx4 v188, v[64:67], s[30:31]
	s_not_b64 s[10:11], s[36:37]
	s_andn2_b64 vcc, exec, s[8:9]
	s_mov_b64 s[8:9], -1
	s_cbranch_vccnz .LBB0_400
	s_and_b64 vcc, exec, s[10:11]
	s_cbranch_vccnz .LBB0_399
	s_barrier
	s_branch .LBB0_399
